# GEMM K-loops: redundant s_setprio 0 / s_setprio 1 pair between the two 16-MFMA halves of each block removed (on top of the transition trimming)
# speedup vs baseline: 1.1012x; 1.1012x over previous
; #define PG8_STAGE(bufoff, gbase, voff) do { _Pragma("unroll") for (int _i = 0; _i < 2; ++_i) \
;         __builtin_amdgcn_global_load_lds((const unsigned*)((const char*)(gbase) + (voff)[_i]), (PG8_LAS unsigned*)(lds + (bufoff) + ldsw + _i * 8192), 16, 0, 0); } while (0)
; #define PG8_LDA(dst, b, h) do { _Pragma("unroll") for (int m = 0; m < 4; ++m) _Pragma("unroll") for (int k = 0; k < 2; ++k) dst[m][k] = *(const PG8_LAS bf16x8*)(lds + PG8_SA(b, h) + aoff + m * 2048 + k * 1024); } while (0)
; #define PG8_LDB(dst, b, h) do { _Pragma("unroll") for (int n = 0; n < 2; ++n) _Pragma("unroll") for (int k = 0; k < 2; ++k) dst[n][k] = *(const PG8_LAS bf16x8*)(lds + PG8_SB(b, h) + boff + n * 2048 + k * 1024); } while (0)
; #define PG8_MMA(ai, bj, At, Bt) do { __builtin_amdgcn_s_setprio(1); _Pragma("unroll") for (int m = 0; m < 4; ++m) _Pragma("unroll") for (int n = 0; n < 2; ++n) _Pragma("unroll") for (int k = 0; k < 2; ++k) \
;         acc[ai][bj][m][n] = __builtin_amdgcn_mfma_f32_16x16x32_bf16(Bt[n][k], At[m][k], acc[ai][bj][m][n], 0, 0, 0); __builtin_amdgcn_s_setprio(0); } while (0)
; #define PG8_WAIT_V(n) asm volatile("s_waitcnt vmcnt(" #n ")" ::: "memory")
; #define PG8_WAIT_L(n) asm volatile("s_waitcnt lgkmcnt(" #n ")" ::: "memory")
; #define PG8_BAR __builtin_amdgcn_s_barrier()
; #define PG8_SCHED __builtin_amdgcn_sched_barrier(0)
; template <class Epi, class Sched, bool ALIGN_EPI = false, bool SP2 = false>
; __device__ __forceinline__ void gemm_phase(PG8_LAS unsigned char* lds, const Gemm g, const Sched& S, const Epi& E) {
;     ...
;             const bool last = (t == nt - 2);
;             const char* a1 = cA + (size_t)(t + 1) * kstep;
;             const char* a2 = last ? nA : cA + (size_t)(t + 2) * kstep; const char* b2 = last ? nB : cB + (size_t)(t + 2) * kstep;
;             const char* a3 = a2 + kstep; const char* b3 = b2 + kstep;
;             if (last && has_next) S.a_ready(nxt);
;             if constexpr (SP2) {
;             PG8_LDB(B0, 0, 0); PG8_LDB(B1, 0, 1); PG8_SCHED; PG8_LDA(At, 0, 0); PG8_STAGE(PG8_SA(1, 1), a1 + hstep, voffA);
;             PG8_WAIT_V(8); PG8_WAIT_L(0); PG8_BAR; PG8_MMA(0, 0, At, B0); PG8_MMA(0, 1, At, B1); PG8_BAR; PG8_SCHED;
;             PG8_LDA(At, 0, 1); PG8_STAGE(PG8_SB(0, 0), b2, voffB); PG8_STAGE(PG8_SB(0, 1), b2 + hstepB, voffB); PG8_STAGE(PG8_SA(0, 0), a2, voffA);
.LBB0_150:
	ds_read_b128 v[156:159], v150
	ds_read_b128 v[160:163], v150 offset:1024
	ds_read_b128 v[164:167], v150 offset:2048
	ds_read_b128 v[168:171], v150 offset:3072
	ds_read_b128 v[172:175], v151
	ds_read_b128 v[176:179], v151 offset:1024
	ds_read_b128 v[180:183], v151 offset:2048
	ds_read_b128 v[184:187], v151 offset:3072
	s_add_u32 s26, s24, 0x4000
	s_addc_u32 s27, s25, 0
	s_cmp_eq_u32 s75, 12
	s_cselect_b32 s40, s71, s26
	s_cselect_b32 s41, s17, s27
	s_cselect_b32 s28, s72, s73
	s_cselect_b32 s29, s15, s74
	s_add_u32 s26, s40, 0x8000
	s_addc_u32 s27, s41, 0
	v_lshl_add_u64 v[216:217], s[24:25], 0, v[140:141]
	s_add_i32 m0, s23, 0xc000
	ds_read_b128 v[188:191], v152
	ds_read_b128 v[192:195], v152 offset:1024
	ds_read_b128 v[196:199], v152 offset:2048
	ds_read_b128 v[200:203], v152 offset:3072
	ds_read_b128 v[204:207], v152 offset:4096
	ds_read_b128 v[208:211], v152 offset:5120
	ds_read_b128 v[212:215], v152 offset:6144
	ds_read_b128 v[220:223], v152 offset:7168
	global_load_lds_dwordx4 v[216:217], off
	v_lshl_add_u64 v[216:217], s[24:25], 0, v[142:143]
	s_add_i32 m0, s23, 0xe000
	s_nop 0
	global_load_lds_dwordx4 v[216:217], off
	s_waitcnt vmcnt(8)
	s_waitcnt lgkmcnt(0)
	s_setprio 1
	s_barrier
	v_mfma_f32_16x16x32_bf16 v[126:129], v[156:159], v[188:191], v[126:129]
	v_mfma_f32_16x16x32_bf16 v[122:125], v[164:167], v[188:191], v[122:125]
	v_mfma_f32_16x16x32_bf16 v[114:117], v[156:159], v[196:199], v[114:117]
	v_mfma_f32_16x16x32_bf16 v[106:109], v[164:167], v[196:199], v[106:109]
	v_mfma_f32_16x16x32_bf16 v[98:101], v[156:159], v[204:207], v[98:101]
	v_mfma_f32_16x16x32_bf16 v[90:93], v[164:167], v[204:207], v[90:93]
	v_mfma_f32_16x16x32_bf16 v[78:81], v[156:159], v[212:215], v[78:81]
	v_mfma_f32_16x16x32_bf16 v[74:77], v[164:167], v[212:215], v[74:77]
	v_mfma_f32_16x16x32_bf16 v[126:129], v[160:163], v[192:195], v[126:129]
	v_mfma_f32_16x16x32_bf16 v[122:125], v[168:171], v[192:195], v[122:125]
	v_mfma_f32_16x16x32_bf16 v[114:117], v[160:163], v[200:203], v[114:117]
	v_mfma_f32_16x16x32_bf16 v[106:109], v[168:171], v[200:203], v[106:109]
	v_mfma_f32_16x16x32_bf16 v[98:101], v[160:163], v[208:211], v[98:101]
	v_mfma_f32_16x16x32_bf16 v[90:93], v[168:171], v[208:211], v[90:93]
	v_mfma_f32_16x16x32_bf16 v[78:81], v[160:163], v[220:223], v[78:81]
	v_mfma_f32_16x16x32_bf16 v[74:77], v[168:171], v[220:223], v[74:77]
	v_mfma_f32_16x16x32_bf16 v[118:121], v[172:175], v[188:191], v[118:121]
	v_mfma_f32_16x16x32_bf16 v[110:113], v[180:183], v[188:191], v[110:113]
	v_mfma_f32_16x16x32_bf16 v[102:105], v[172:175], v[196:199], v[102:105]
	v_mfma_f32_16x16x32_bf16 v[94:97], v[180:183], v[196:199], v[94:97]
	v_mfma_f32_16x16x32_bf16 v[86:89], v[172:175], v[204:207], v[86:89]
	v_mfma_f32_16x16x32_bf16 v[82:85], v[180:183], v[204:207], v[82:85]
	v_mfma_f32_16x16x32_bf16 v[70:73], v[172:175], v[212:215], v[70:73]
	v_mfma_f32_16x16x32_bf16 v[66:69], v[180:183], v[212:215], v[66:69]
	v_mfma_f32_16x16x32_bf16 v[118:121], v[176:179], v[192:195], v[118:121]
	v_mfma_f32_16x16x32_bf16 v[110:113], v[184:187], v[192:195], v[110:113]
	v_mfma_f32_16x16x32_bf16 v[102:105], v[176:179], v[200:203], v[102:105]
	v_mfma_f32_16x16x32_bf16 v[94:97], v[184:187], v[200:203], v[94:97]
	v_mfma_f32_16x16x32_bf16 v[86:89], v[176:179], v[208:211], v[86:89]
	v_mfma_f32_16x16x32_bf16 v[82:85], v[184:187], v[208:211], v[82:85]
	v_mfma_f32_16x16x32_bf16 v[70:73], v[176:179], v[220:223], v[70:73]
	v_mfma_f32_16x16x32_bf16 v[66:69], v[184:187], v[220:223], v[66:69]
	s_barrier
	s_setprio 0
	s_add_i32 s76, s56, s0
	v_lshl_add_u64 v[216:217], s[28:29], 0, v[134:135]
	s_mov_b32 m0, s76
	ds_read_b128 v[188:191], v152 offset:16384
	ds_read_b128 v[192:195], v152 offset:17408
	ds_read_b128 v[196:199], v152 offset:18432
	ds_read_b128 v[200:203], v152 offset:19456
	ds_read_b128 v[204:207], v152 offset:20480
	ds_read_b128 v[208:211], v152 offset:21504
	ds_read_b128 v[212:215], v152 offset:22528
	ds_read_b128 v[220:223], v152 offset:23552
	global_load_lds_dwordx4 v[216:217], off
	s_add_i32 m0, s76, 0x2000
	s_add_u32 s76, s28, 0x1000
	v_lshl_add_u64 v[216:217], s[28:29], 0, v[130:131]
	s_addc_u32 s77, s29, 0
	s_add_i32 s78, s57, s0
	global_load_lds_dwordx4 v[216:217], off
	v_lshl_add_u64 v[216:217], s[76:77], 0, v[134:135]
	s_mov_b32 m0, s78
	s_nop 0
	global_load_lds_dwordx4 v[216:217], off
	v_lshl_add_u64 v[216:217], s[76:77], 0, v[130:131]
	s_add_i32 m0, s78, 0x2000
	s_nop 0
	global_load_lds_dwordx4 v[216:217], off
	v_lshl_add_u64 v[216:217], s[40:41], 0, v[136:137]
	s_mov_b32 m0, s23
	s_nop 0
	global_load_lds_dwordx4 v[216:217], off
	v_lshl_add_u64 v[216:217], s[40:41], 0, v[132:133]
	s_mov_b32 m0, s49
	s_nop 0
	global_load_lds_dwordx4 v[216:217], off
	s_waitcnt vmcnt(8)
	s_waitcnt lgkmcnt(0)
	s_setprio 1
	s_barrier
; #define PG8_STAGE(bufoff, gbase, voff) do { _Pragma("unroll") for (int _i = 0; _i < 2; ++_i) \
;         __builtin_amdgcn_global_load_lds((const unsigned*)((const char*)(gbase) + (voff)[_i]), (PG8_LAS unsigned*)(lds + (bufoff) + ldsw + _i * 8192), 16, 0, 0); } while (0)
; #define PG8_LDA(dst, b, h) do { _Pragma("unroll") for (int m = 0; m < 4; ++m) _Pragma("unroll") for (int k = 0; k < 2; ++k) dst[m][k] = *(const PG8_LAS bf16x8*)(lds + PG8_SA(b, h) + aoff + m * 2048 + k * 1024); } while (0)
; #define PG8_LDB(dst, b, h) do { _Pragma("unroll") for (int n = 0; n < 2; ++n) _Pragma("unroll") for (int k = 0; k < 2; ++k) dst[n][k] = *(const PG8_LAS bf16x8*)(lds + PG8_SB(b, h) + boff + n * 2048 + k * 1024); } while (0)
; #define PG8_MMA(ai, bj, At, Bt) do { __builtin_amdgcn_s_setprio(1); _Pragma("unroll") for (int m = 0; m < 4; ++m) _Pragma("unroll") for (int n = 0; n < 2; ++n) _Pragma("unroll") for (int k = 0; k < 2; ++k) \
;         acc[ai][bj][m][n] = __builtin_amdgcn_mfma_f32_16x16x32_bf16(Bt[n][k], At[m][k], acc[ai][bj][m][n], 0, 0, 0); __builtin_amdgcn_s_setprio(0); } while (0)
; #define PG8_WAIT_V(n) asm volatile("s_waitcnt vmcnt(" #n ")" ::: "memory")
; #define PG8_WAIT_L(n) asm volatile("s_waitcnt lgkmcnt(" #n ")" ::: "memory")
; #define PG8_BAR __builtin_amdgcn_s_barrier()
; #define PG8_SCHED __builtin_amdgcn_sched_barrier(0)
; template <class Epi, class Sched, bool ALIGN_EPI = false, bool SP2 = false>
; __device__ __forceinline__ void gemm_phase(PG8_LAS unsigned char* lds, const Gemm g, const Sched& S, const Epi& E) {
;     ...
;             PG8_LDA(At, 0, 1); PG8_STAGE(PG8_SB(0, 0), b2, voffB); PG8_STAGE(PG8_SB(0, 1), b2 + hstepB, voffB); PG8_STAGE(PG8_SA(0, 0), a2, voffA);
;             PG8_WAIT_V(8); PG8_WAIT_L(0); PG8_BAR; PG8_MMA(1, 0, At, B0); PG8_MMA(1, 1, At, B1); PG8_BAR; PG8_SCHED;
;             PG8_LDB(B0, 1, 0); PG8_LDB(B1, 1, 1); PG8_SCHED; PG8_LDA(At, 1, 0); PG8_STAGE(PG8_SA(0, 1), a2 + hstep, voffA);
;             PG8_WAIT_V(8); PG8_WAIT_L(0); PG8_BAR; PG8_MMA(0, 0, At, B0); PG8_MMA(0, 1, At, B1); PG8_BAR; PG8_SCHED;
	v_mfma_f32_16x16x32_bf16 v[62:65], v[156:159], v[188:191], v[62:65]
	v_mfma_f32_16x16x32_bf16 v[58:61], v[164:167], v[188:191], v[58:61]
	v_mfma_f32_16x16x32_bf16 v[46:49], v[156:159], v[196:199], v[46:49]
	v_mfma_f32_16x16x32_bf16 v[42:45], v[164:167], v[196:199], v[42:45]
	v_mfma_f32_16x16x32_bf16 v[34:37], v[156:159], v[204:207], v[34:37]
	v_mfma_f32_16x16x32_bf16 v[26:29], v[164:167], v[204:207], v[26:29]
	v_mfma_f32_16x16x32_bf16 v[18:21], v[156:159], v[212:215], v[18:21]
	v_mfma_f32_16x16x32_bf16 v[10:13], v[164:167], v[212:215], v[10:13]
	v_mfma_f32_16x16x32_bf16 v[62:65], v[160:163], v[192:195], v[62:65]
	v_mfma_f32_16x16x32_bf16 v[58:61], v[168:171], v[192:195], v[58:61]
	v_mfma_f32_16x16x32_bf16 v[46:49], v[160:163], v[200:203], v[46:49]
	v_mfma_f32_16x16x32_bf16 v[42:45], v[168:171], v[200:203], v[42:45]
	v_mfma_f32_16x16x32_bf16 v[34:37], v[160:163], v[208:211], v[34:37]
	v_mfma_f32_16x16x32_bf16 v[26:29], v[168:171], v[208:211], v[26:29]
	v_mfma_f32_16x16x32_bf16 v[18:21], v[160:163], v[220:223], v[18:21]
	v_mfma_f32_16x16x32_bf16 v[10:13], v[168:171], v[220:223], v[10:13]
	v_mfma_f32_16x16x32_bf16 v[54:57], v[172:175], v[188:191], v[54:57]
	v_mfma_f32_16x16x32_bf16 v[50:53], v[180:183], v[188:191], v[50:53]
	v_mfma_f32_16x16x32_bf16 v[38:41], v[172:175], v[196:199], v[38:41]
	v_mfma_f32_16x16x32_bf16 v[30:33], v[180:183], v[196:199], v[30:33]
	v_mfma_f32_16x16x32_bf16 v[22:25], v[172:175], v[204:207], v[22:25]
	v_mfma_f32_16x16x32_bf16 v[14:17], v[180:183], v[204:207], v[14:17]
	v_mfma_f32_16x16x32_bf16 v[6:9], v[172:175], v[212:215], v[6:9]
	v_mfma_f32_16x16x32_bf16 v[2:5], v[180:183], v[212:215], v[2:5]
	v_mfma_f32_16x16x32_bf16 v[54:57], v[176:179], v[192:195], v[54:57]
	v_mfma_f32_16x16x32_bf16 v[50:53], v[184:187], v[192:195], v[50:53]
	v_mfma_f32_16x16x32_bf16 v[38:41], v[176:179], v[200:203], v[38:41]
	v_mfma_f32_16x16x32_bf16 v[30:33], v[184:187], v[200:203], v[30:33]
	v_mfma_f32_16x16x32_bf16 v[22:25], v[176:179], v[208:211], v[22:25]
	v_mfma_f32_16x16x32_bf16 v[14:17], v[184:187], v[208:211], v[14:17]
	v_mfma_f32_16x16x32_bf16 v[6:9], v[176:179], v[220:223], v[6:9]
	v_mfma_f32_16x16x32_bf16 v[2:5], v[184:187], v[220:223], v[2:5]
	s_barrier
	s_setprio 0
	s_add_i32 s76, 0, 0x18000
	v_add_u32_e32 v148, s76, v149
	s_add_i32 s77, 0, 0x1c000
	ds_read_b128 v[156:159], v148
	ds_read_b128 v[160:163], v148 offset:1024
	ds_read_b128 v[164:167], v148 offset:2048
	ds_read_b128 v[168:171], v148 offset:3072
	v_add_u32_e32 v148, s77, v149
	ds_read_b128 v[172:175], v148
	ds_read_b128 v[176:179], v148 offset:1024
	ds_read_b128 v[180:183], v148 offset:2048
	ds_read_b128 v[184:187], v148 offset:3072
	s_add_u32 s40, s40, 0x4000
	s_addc_u32 s41, s41, 0
	s_mov_b32 m0, s50
	v_lshl_add_u64 v[216:217], s[40:41], 0, v[136:137]
	ds_read_b128 v[188:191], v152 offset:32768
	ds_read_b128 v[192:195], v152 offset:33792
	ds_read_b128 v[196:199], v152 offset:34816
	ds_read_b128 v[200:203], v152 offset:35840
	ds_read_b128 v[204:207], v152 offset:36864
	ds_read_b128 v[208:211], v152 offset:37888
	ds_read_b128 v[212:215], v152 offset:38912
	ds_read_b128 v[220:223], v152 offset:39936
	global_load_lds_dwordx4 v[216:217], off
	v_lshl_add_u64 v[216:217], s[40:41], 0, v[132:133]
	s_mov_b32 m0, s51
	s_nop 0
	global_load_lds_dwordx4 v[216:217], off
	s_waitcnt vmcnt(8)
	s_waitcnt lgkmcnt(0)
	s_setprio 1
	s_barrier
	v_mfma_f32_16x16x32_bf16 v[126:129], v[156:159], v[188:191], v[126:129]
	v_mfma_f32_16x16x32_bf16 v[122:125], v[164:167], v[188:191], v[122:125]
	v_mfma_f32_16x16x32_bf16 v[114:117], v[156:159], v[196:199], v[114:117]
	v_mfma_f32_16x16x32_bf16 v[106:109], v[164:167], v[196:199], v[106:109]
	v_mfma_f32_16x16x32_bf16 v[98:101], v[156:159], v[204:207], v[98:101]
	v_mfma_f32_16x16x32_bf16 v[90:93], v[164:167], v[204:207], v[90:93]
	v_mfma_f32_16x16x32_bf16 v[78:81], v[156:159], v[212:215], v[78:81]
	v_mfma_f32_16x16x32_bf16 v[74:77], v[164:167], v[212:215], v[74:77]
	v_mfma_f32_16x16x32_bf16 v[126:129], v[160:163], v[192:195], v[126:129]
	v_mfma_f32_16x16x32_bf16 v[122:125], v[168:171], v[192:195], v[122:125]
	v_mfma_f32_16x16x32_bf16 v[114:117], v[160:163], v[200:203], v[114:117]
	v_mfma_f32_16x16x32_bf16 v[106:109], v[168:171], v[200:203], v[106:109]
	v_mfma_f32_16x16x32_bf16 v[98:101], v[160:163], v[208:211], v[98:101]
	v_mfma_f32_16x16x32_bf16 v[90:93], v[168:171], v[208:211], v[90:93]
	v_mfma_f32_16x16x32_bf16 v[78:81], v[160:163], v[220:223], v[78:81]
	v_mfma_f32_16x16x32_bf16 v[74:77], v[168:171], v[220:223], v[74:77]
	v_mfma_f32_16x16x32_bf16 v[118:121], v[172:175], v[188:191], v[118:121]
	v_mfma_f32_16x16x32_bf16 v[110:113], v[180:183], v[188:191], v[110:113]
	v_mfma_f32_16x16x32_bf16 v[102:105], v[172:175], v[196:199], v[102:105]
	v_mfma_f32_16x16x32_bf16 v[94:97], v[180:183], v[196:199], v[94:97]
	v_mfma_f32_16x16x32_bf16 v[86:89], v[172:175], v[204:207], v[86:89]
	v_mfma_f32_16x16x32_bf16 v[82:85], v[180:183], v[204:207], v[82:85]
	v_mfma_f32_16x16x32_bf16 v[70:73], v[172:175], v[212:215], v[70:73]
	v_mfma_f32_16x16x32_bf16 v[66:69], v[180:183], v[212:215], v[66:69]
	v_mfma_f32_16x16x32_bf16 v[118:121], v[176:179], v[192:195], v[118:121]
	v_mfma_f32_16x16x32_bf16 v[110:113], v[184:187], v[192:195], v[110:113]
	v_mfma_f32_16x16x32_bf16 v[102:105], v[176:179], v[200:203], v[102:105]
	v_mfma_f32_16x16x32_bf16 v[94:97], v[184:187], v[200:203], v[94:97]
	v_mfma_f32_16x16x32_bf16 v[86:89], v[176:179], v[208:211], v[86:89]
	v_mfma_f32_16x16x32_bf16 v[82:85], v[184:187], v[208:211], v[82:85]
	v_mfma_f32_16x16x32_bf16 v[70:73], v[176:179], v[220:223], v[70:73]
	v_mfma_f32_16x16x32_bf16 v[66:69], v[184:187], v[220:223], v[66:69]
	s_barrier
; #define PG8_STAGE(bufoff, gbase, voff) do { _Pragma("unroll") for (int _i = 0; _i < 2; ++_i) \
;         __builtin_amdgcn_global_load_lds((const unsigned*)((const char*)(gbase) + (voff)[_i]), (PG8_LAS unsigned*)(lds + (bufoff) + ldsw + _i * 8192), 16, 0, 0); } while (0)
; #define PG8_LDA(dst, b, h) do { _Pragma("unroll") for (int m = 0; m < 4; ++m) _Pragma("unroll") for (int k = 0; k < 2; ++k) dst[m][k] = *(const PG8_LAS bf16x8*)(lds + PG8_SA(b, h) + aoff + m * 2048 + k * 1024); } while (0)
; #define PG8_MMA(ai, bj, At, Bt) do { __builtin_amdgcn_s_setprio(1); _Pragma("unroll") for (int m = 0; m < 4; ++m) _Pragma("unroll") for (int n = 0; n < 2; ++n) _Pragma("unroll") for (int k = 0; k < 2; ++k) \
;         acc[ai][bj][m][n] = __builtin_amdgcn_mfma_f32_16x16x32_bf16(Bt[n][k], At[m][k], acc[ai][bj][m][n], 0, 0, 0); __builtin_amdgcn_s_setprio(0); } while (0)
; #define PG8_WAIT_V(n) asm volatile("s_waitcnt vmcnt(" #n ")" ::: "memory")
; #define PG8_WAIT_L(n) asm volatile("s_waitcnt lgkmcnt(" #n ")" ::: "memory")
; #define PG8_BAR __builtin_amdgcn_s_barrier()
; #define PG8_SCHED __builtin_amdgcn_sched_barrier(0)
; template <class Epi, class Sched, bool ALIGN_EPI = false, bool SP2 = false>
; __device__ __forceinline__ void gemm_phase(PG8_LAS unsigned char* lds, const Gemm g, const Sched& S, const Epi& E) {
;     ...
;             PG8_LDA(At, 1, 1); PG8_STAGE(PG8_SB(1, 0), b3, voffB); PG8_STAGE(PG8_SB(1, 1), b3 + hstepB, voffB); PG8_STAGE(PG8_SA(1, 0), a3, voffA);
;             PG8_WAIT_V(8); PG8_WAIT_L(0); PG8_BAR; PG8_MMA(1, 0, At, B0); PG8_MMA(1, 1, At, B1); PG8_BAR; PG8_SCHED;
;     ...
;         if constexpr (ALIGN_EPI) { if (wr == 0) PG8_BAR; }
	s_setprio 0
	s_add_u32 s40, s28, 0x8000
	s_addc_u32 s41, s29, 0
	s_add_i32 s76, s76, s0
	v_lshl_add_u64 v[216:217], s[40:41], 0, v[134:135]
	s_mov_b32 m0, s76
	ds_read_b128 v[188:191], v152 offset:49152
	ds_read_b128 v[192:195], v152 offset:50176
	ds_read_b128 v[196:199], v152 offset:51200
	ds_read_b128 v[200:203], v152 offset:52224
	ds_read_b128 v[204:207], v152 offset:53248
	ds_read_b128 v[208:211], v152 offset:54272
	ds_read_b128 v[212:215], v152 offset:55296
	ds_read_b128 v[220:223], v152 offset:56320
	global_load_lds_dwordx4 v[216:217], off
	s_add_i32 m0, s76, 0x2000
	s_add_u32 s28, s28, 0x9000
	v_lshl_add_u64 v[216:217], s[40:41], 0, v[130:131]
	s_addc_u32 s29, s29, 0
	s_add_i32 s40, s77, s0
	global_load_lds_dwordx4 v[216:217], off
	v_lshl_add_u64 v[216:217], s[28:29], 0, v[134:135]
	s_mov_b32 m0, s40
	s_nop 0
	global_load_lds_dwordx4 v[216:217], off
	v_lshl_add_u64 v[216:217], s[28:29], 0, v[130:131]
	s_add_i32 m0, s40, 0x2000
	s_nop 0
	global_load_lds_dwordx4 v[216:217], off
	v_lshl_add_u64 v[216:217], s[26:27], 0, v[136:137]
	s_mov_b32 m0, s54
	s_nop 0
	global_load_lds_dwordx4 v[216:217], off
	v_lshl_add_u64 v[216:217], s[26:27], 0, v[132:133]
	s_mov_b32 m0, s55
	s_nop 0
	global_load_lds_dwordx4 v[216:217], off
	s_waitcnt vmcnt(8)
	s_waitcnt lgkmcnt(0)
	s_setprio 1
	s_barrier
	v_mfma_f32_16x16x32_bf16 v[62:65], v[156:159], v[188:191], v[62:65]
	v_mfma_f32_16x16x32_bf16 v[58:61], v[164:167], v[188:191], v[58:61]
	v_mfma_f32_16x16x32_bf16 v[46:49], v[156:159], v[196:199], v[46:49]
	v_mfma_f32_16x16x32_bf16 v[42:45], v[164:167], v[196:199], v[42:45]
	v_mfma_f32_16x16x32_bf16 v[34:37], v[156:159], v[204:207], v[34:37]
	v_mfma_f32_16x16x32_bf16 v[26:29], v[164:167], v[204:207], v[26:29]
	v_mfma_f32_16x16x32_bf16 v[18:21], v[156:159], v[212:215], v[18:21]
	v_mfma_f32_16x16x32_bf16 v[10:13], v[164:167], v[212:215], v[10:13]
	v_mfma_f32_16x16x32_bf16 v[62:65], v[160:163], v[192:195], v[62:65]
	v_mfma_f32_16x16x32_bf16 v[58:61], v[168:171], v[192:195], v[58:61]
	v_mfma_f32_16x16x32_bf16 v[46:49], v[160:163], v[200:203], v[46:49]
	v_mfma_f32_16x16x32_bf16 v[42:45], v[168:171], v[200:203], v[42:45]
	v_mfma_f32_16x16x32_bf16 v[34:37], v[160:163], v[208:211], v[34:37]
	v_mfma_f32_16x16x32_bf16 v[26:29], v[168:171], v[208:211], v[26:29]
	v_mfma_f32_16x16x32_bf16 v[18:21], v[160:163], v[220:223], v[18:21]
	v_mfma_f32_16x16x32_bf16 v[10:13], v[168:171], v[220:223], v[10:13]
	v_mfma_f32_16x16x32_bf16 v[54:57], v[172:175], v[188:191], v[54:57]
	v_mfma_f32_16x16x32_bf16 v[50:53], v[180:183], v[188:191], v[50:53]
	v_mfma_f32_16x16x32_bf16 v[38:41], v[172:175], v[196:199], v[38:41]
	v_mfma_f32_16x16x32_bf16 v[30:33], v[180:183], v[196:199], v[30:33]
	v_mfma_f32_16x16x32_bf16 v[22:25], v[172:175], v[204:207], v[22:25]
	v_mfma_f32_16x16x32_bf16 v[14:17], v[180:183], v[204:207], v[14:17]
	v_mfma_f32_16x16x32_bf16 v[6:9], v[172:175], v[212:215], v[6:9]
	v_mfma_f32_16x16x32_bf16 v[2:5], v[180:183], v[212:215], v[2:5]
	v_mfma_f32_16x16x32_bf16 v[54:57], v[176:179], v[192:195], v[54:57]
	v_mfma_f32_16x16x32_bf16 v[50:53], v[184:187], v[192:195], v[50:53]
	v_mfma_f32_16x16x32_bf16 v[38:41], v[176:179], v[200:203], v[38:41]
	v_mfma_f32_16x16x32_bf16 v[30:33], v[184:187], v[200:203], v[30:33]
	v_mfma_f32_16x16x32_bf16 v[22:25], v[176:179], v[208:211], v[22:25]
	v_mfma_f32_16x16x32_bf16 v[14:17], v[184:187], v[208:211], v[14:17]
	v_mfma_f32_16x16x32_bf16 v[6:9], v[176:179], v[220:223], v[6:9]
	v_mfma_f32_16x16x32_bf16 v[2:5], v[184:187], v[220:223], v[2:5]
	s_barrier
	s_setprio 0
	s_add_i32 s75, s75, 2
	s_add_u32 s24, s24, 0x10000
	s_addc_u32 s25, s25, 0
	s_add_u32 s73, s73, 0x10000
	s_addc_u32 s74, s74, 0
	s_cmp_gt_u32 s75, 13
	s_cbranch_scc0 .LBB0_150
	s_and_b64 vcc, exec, s[12:13]
	s_cbranch_vccz .LBB0_153
	s_barrier

; #define PG8_STAGE(bufoff, gbase, voff) do { _Pragma("unroll") for (int _i = 0; _i < 2; ++_i) \
;         __builtin_amdgcn_global_load_lds((const unsigned*)((const char*)(gbase) + (voff)[_i]), (PG8_LAS unsigned*)(lds + (bufoff) + ldsw + _i * 8192), 16, 0, 0); } while (0)
; #define PG8_LDA(dst, b, h) do { _Pragma("unroll") for (int m = 0; m < 4; ++m) _Pragma("unroll") for (int k = 0; k < 2; ++k) dst[m][k] = *(const PG8_LAS bf16x8*)(lds + PG8_SA(b, h) + aoff + m * 2048 + k * 1024); } while (0)
; #define PG8_LDB(dst, b, h) do { _Pragma("unroll") for (int n = 0; n < 2; ++n) _Pragma("unroll") for (int k = 0; k < 2; ++k) dst[n][k] = *(const PG8_LAS bf16x8*)(lds + PG8_SB(b, h) + boff + n * 2048 + k * 1024); } while (0)
; #define PG8_MMA(ai, bj, At, Bt) do { __builtin_amdgcn_s_setprio(1); _Pragma("unroll") for (int m = 0; m < 4; ++m) _Pragma("unroll") for (int n = 0; n < 2; ++n) _Pragma("unroll") for (int k = 0; k < 2; ++k) \
;         acc[ai][bj][m][n] = __builtin_amdgcn_mfma_f32_16x16x32_bf16(Bt[n][k], At[m][k], acc[ai][bj][m][n], 0, 0, 0); __builtin_amdgcn_s_setprio(0); } while (0)
; #define PG8_WAIT_V(n) asm volatile("s_waitcnt vmcnt(" #n ")" ::: "memory")
; #define PG8_WAIT_L(n) asm volatile("s_waitcnt lgkmcnt(" #n ")" ::: "memory")
; #define PG8_BAR __builtin_amdgcn_s_barrier()
; template <class Epi, class Sched, bool ALIGN_EPI = false, bool SP2 = false>
; __device__ __forceinline__ void gemm_phase(PG8_LAS unsigned char* lds, const Gemm g, const Sched& S, const Epi& E) {
;     ...
;             const char* a1 = cA + (size_t)(t + 1) * kstep;
;             const char* a2 = last ? nA : cA + (size_t)(t + 2) * kstep; const char* b2 = last ? nB : cB + (size_t)(t + 2) * kstep;
;             const char* a3 = a2 + kstep; const char* b3 = b2 + kstep;
;             if (last && has_next) S.a_ready(nxt);
;             if constexpr (SP2) {
;             PG8_LDB(B0, 0, 0); PG8_LDB(B1, 0, 1); PG8_SCHED; PG8_LDA(At, 0, 0); PG8_STAGE(PG8_SA(1, 1), a1 + hstep, voffA);
;             PG8_WAIT_V(8); PG8_WAIT_L(0); PG8_BAR; PG8_MMA(0, 0, At, B0); PG8_MMA(0, 1, At, B1); PG8_BAR; PG8_SCHED;
;             PG8_LDA(At, 0, 1); PG8_STAGE(PG8_SB(0, 0), b2, voffB); PG8_STAGE(PG8_SB(0, 1), b2 + hstepB, voffB); PG8_STAGE(PG8_SA(0, 0), a2, voffA);
;             PG8_WAIT_V(8); PG8_WAIT_L(0); PG8_BAR; PG8_MMA(1, 0, At, B0); PG8_MMA(1, 1, At, B1); PG8_BAR; PG8_SCHED;
.LBB0_380:
	s_add_u32 s48, s28, s46
	v_add_u32_e32 v3, s87, v221
	s_addc_u32 s49, s29, s47
	ds_read_b128 v[134:137], v3
	ds_read_b128 v[138:141], v3 offset:1024
	ds_read_b128 v[142:145], v3 offset:2048
	ds_read_b128 v[146:149], v3 offset:3072
	v_add_u32_e32 v3, s88, v221
	s_add_u32 s48, s48, 0x10000
	ds_read_b128 v[150:153], v3
	ds_read_b128 v[154:157], v3 offset:1024
	ds_read_b128 v[158:161], v3 offset:2048
	ds_read_b128 v[162:165], v3 offset:3072
	s_addc_u32 s49, s49, 0
	s_add_u32 s50, s27, s46
	s_addc_u32 s51, s45, s47
	s_cmp_eq_u32 s46, 0x70000
	s_cselect_b32 s70, s1, s48
	s_cselect_b32 s71, s0, s49
	s_cselect_b32 s50, s21, s50
	s_cselect_b32 s51, s19, s51
	s_add_u32 s48, s70, 0x8000
	s_addc_u32 s49, s71, 0
	v_lshl_add_u64 v[4:5], v[182:183], 0, s[46:47]
	s_add_i32 m0, s74, 0xc000
	ds_read_b128 v[166:169], v225
	ds_read_b128 v[170:173], v225 offset:1024
	ds_read_b128 v[174:177], v225 offset:2048
	ds_read_b128 v[178:181], v225 offset:3072
	ds_read_b128 v[186:189], v225 offset:4096
	ds_read_b128 v[190:193], v225 offset:5120
	ds_read_b128 v[194:197], v225 offset:6144
	ds_read_b128 v[228:231], v225 offset:7168
	global_load_lds_dwordx4 v[4:5], off
	v_lshl_add_u64 v[4:5], v[184:185], 0, s[46:47]
	s_add_i32 m0, s74, 0xe000
	s_nop 0
	global_load_lds_dwordx4 v[4:5], off
	s_waitcnt vmcnt(8)
	s_waitcnt lgkmcnt(0)
	s_setprio 1
	s_barrier
	v_mfma_f32_16x16x32_bf16 v[130:133], v[134:137], v[166:169], v[130:133]
	v_mfma_f32_16x16x32_bf16 v[126:129], v[142:145], v[166:169], v[126:129]
	v_mfma_f32_16x16x32_bf16 v[114:117], v[134:137], v[174:177], v[114:117]
	v_mfma_f32_16x16x32_bf16 v[110:113], v[142:145], v[174:177], v[110:113]
	v_mfma_f32_16x16x32_bf16 v[98:101], v[134:137], v[186:189], v[98:101]
	v_mfma_f32_16x16x32_bf16 v[94:97], v[142:145], v[186:189], v[94:97]
	v_mfma_f32_16x16x32_bf16 v[82:85], v[134:137], v[194:197], v[82:85]
	v_mfma_f32_16x16x32_bf16 v[78:81], v[142:145], v[194:197], v[78:81]
	v_mfma_f32_16x16x32_bf16 v[130:133], v[138:141], v[170:173], v[130:133]
	v_mfma_f32_16x16x32_bf16 v[126:129], v[146:149], v[170:173], v[126:129]
	v_mfma_f32_16x16x32_bf16 v[114:117], v[138:141], v[178:181], v[114:117]
	v_mfma_f32_16x16x32_bf16 v[110:113], v[146:149], v[178:181], v[110:113]
	v_mfma_f32_16x16x32_bf16 v[98:101], v[138:141], v[190:193], v[98:101]
	v_mfma_f32_16x16x32_bf16 v[94:97], v[146:149], v[190:193], v[94:97]
	v_mfma_f32_16x16x32_bf16 v[82:85], v[138:141], v[228:231], v[82:85]
	v_mfma_f32_16x16x32_bf16 v[78:81], v[146:149], v[228:231], v[78:81]
	v_mfma_f32_16x16x32_bf16 v[122:125], v[150:153], v[166:169], v[122:125]
	v_mfma_f32_16x16x32_bf16 v[118:121], v[158:161], v[166:169], v[118:121]
	v_mfma_f32_16x16x32_bf16 v[106:109], v[150:153], v[174:177], v[106:109]
	v_mfma_f32_16x16x32_bf16 v[102:105], v[158:161], v[174:177], v[102:105]
	v_mfma_f32_16x16x32_bf16 v[90:93], v[150:153], v[186:189], v[90:93]
	v_mfma_f32_16x16x32_bf16 v[86:89], v[158:161], v[186:189], v[86:89]
	v_mfma_f32_16x16x32_bf16 v[74:77], v[150:153], v[194:197], v[74:77]
	v_mfma_f32_16x16x32_bf16 v[70:73], v[158:161], v[194:197], v[70:73]
	v_mfma_f32_16x16x32_bf16 v[122:125], v[154:157], v[170:173], v[122:125]
	v_mfma_f32_16x16x32_bf16 v[118:121], v[162:165], v[170:173], v[118:121]
	v_mfma_f32_16x16x32_bf16 v[106:109], v[154:157], v[178:181], v[106:109]
	v_mfma_f32_16x16x32_bf16 v[102:105], v[162:165], v[178:181], v[102:105]
	v_mfma_f32_16x16x32_bf16 v[90:93], v[154:157], v[190:193], v[90:93]
	v_mfma_f32_16x16x32_bf16 v[86:89], v[162:165], v[190:193], v[86:89]
	v_mfma_f32_16x16x32_bf16 v[74:77], v[154:157], v[228:231], v[74:77]
	v_mfma_f32_16x16x32_bf16 v[70:73], v[162:165], v[228:231], v[70:73]
	s_barrier
	s_setprio 0
	s_add_i32 s52, s87, s73
	v_lshl_add_u64 v[4:5], s[50:51], 0, v[200:201]
	s_mov_b32 m0, s52
	ds_read_b128 v[166:169], v225 offset:16384
	ds_read_b128 v[170:173], v225 offset:17408
	ds_read_b128 v[174:177], v225 offset:18432
	ds_read_b128 v[178:181], v225 offset:19456
	ds_read_b128 v[186:189], v225 offset:20480
	ds_read_b128 v[190:193], v225 offset:21504
	ds_read_b128 v[194:197], v225 offset:22528
	ds_read_b128 v[228:231], v225 offset:23552
	global_load_lds_dwordx4 v[4:5], off
	s_add_i32 m0, s52, 0x2000
	s_add_u32 s52, s50, 0x1000
	v_lshl_add_u64 v[4:5], s[50:51], 0, v[204:205]
	s_addc_u32 s53, s51, 0
	s_add_i32 s54, s88, s73
	global_load_lds_dwordx4 v[4:5], off
	v_lshl_add_u64 v[4:5], s[52:53], 0, v[200:201]
	s_mov_b32 m0, s54
	s_nop 0
	global_load_lds_dwordx4 v[4:5], off
	v_lshl_add_u64 v[4:5], s[52:53], 0, v[204:205]
	s_add_i32 m0, s54, 0x2000
	s_nop 0
	global_load_lds_dwordx4 v[4:5], off
	v_lshl_add_u64 v[4:5], s[70:71], 0, v[198:199]
	s_mov_b32 m0, s74
	s_nop 0
	global_load_lds_dwordx4 v[4:5], off
	v_lshl_add_u64 v[4:5], s[70:71], 0, v[202:203]
	s_mov_b32 m0, s75
	s_nop 0
	global_load_lds_dwordx4 v[4:5], off
	s_waitcnt vmcnt(8)
	s_waitcnt lgkmcnt(0)
	s_setprio 1
	s_barrier
; #define PG8_STAGE(bufoff, gbase, voff) do { _Pragma("unroll") for (int _i = 0; _i < 2; ++_i) \
;         __builtin_amdgcn_global_load_lds((const unsigned*)((const char*)(gbase) + (voff)[_i]), (PG8_LAS unsigned*)(lds + (bufoff) + ldsw + _i * 8192), 16, 0, 0); } while (0)
; #define PG8_LDA(dst, b, h) do { _Pragma("unroll") for (int m = 0; m < 4; ++m) _Pragma("unroll") for (int k = 0; k < 2; ++k) dst[m][k] = *(const PG8_LAS bf16x8*)(lds + PG8_SA(b, h) + aoff + m * 2048 + k * 1024); } while (0)
; #define PG8_LDB(dst, b, h) do { _Pragma("unroll") for (int n = 0; n < 2; ++n) _Pragma("unroll") for (int k = 0; k < 2; ++k) dst[n][k] = *(const PG8_LAS bf16x8*)(lds + PG8_SB(b, h) + boff + n * 2048 + k * 1024); } while (0)
; #define PG8_MMA(ai, bj, At, Bt) do { __builtin_amdgcn_s_setprio(1); _Pragma("unroll") for (int m = 0; m < 4; ++m) _Pragma("unroll") for (int n = 0; n < 2; ++n) _Pragma("unroll") for (int k = 0; k < 2; ++k) \
;         acc[ai][bj][m][n] = __builtin_amdgcn_mfma_f32_16x16x32_bf16(Bt[n][k], At[m][k], acc[ai][bj][m][n], 0, 0, 0); __builtin_amdgcn_s_setprio(0); } while (0)
; #define PG8_WAIT_V(n) asm volatile("s_waitcnt vmcnt(" #n ")" ::: "memory")
; #define PG8_WAIT_L(n) asm volatile("s_waitcnt lgkmcnt(" #n ")" ::: "memory")
; #define PG8_BAR __builtin_amdgcn_s_barrier()
; #define PG8_SCHED __builtin_amdgcn_sched_barrier(0)
; template <class Epi, class Sched, bool ALIGN_EPI = false, bool SP2 = false>
; __device__ __forceinline__ void gemm_phase(PG8_LAS unsigned char* lds, const Gemm g, const Sched& S, const Epi& E) {
;     ...
;             PG8_WAIT_V(8); PG8_WAIT_L(0); PG8_BAR; PG8_MMA(1, 0, At, B0); PG8_MMA(1, 1, At, B1); PG8_BAR; PG8_SCHED;
;             PG8_LDB(B0, 1, 0); PG8_LDB(B1, 1, 1); PG8_SCHED; PG8_LDA(At, 1, 0); PG8_STAGE(PG8_SA(0, 1), a2 + hstep, voffA);
;             PG8_WAIT_V(8); PG8_WAIT_L(0); PG8_BAR; PG8_MMA(0, 0, At, B0); PG8_MMA(0, 1, At, B1); PG8_BAR; PG8_SCHED;
	v_mfma_f32_16x16x32_bf16 v[66:69], v[134:137], v[166:169], v[66:69]
	v_mfma_f32_16x16x32_bf16 v[62:65], v[142:145], v[166:169], v[62:65]
	v_mfma_f32_16x16x32_bf16 v[50:53], v[134:137], v[174:177], v[50:53]
	v_mfma_f32_16x16x32_bf16 v[46:49], v[142:145], v[174:177], v[46:49]
	v_mfma_f32_16x16x32_bf16 v[34:37], v[134:137], v[186:189], v[34:37]
	v_mfma_f32_16x16x32_bf16 v[30:33], v[142:145], v[186:189], v[30:33]
	v_mfma_f32_16x16x32_bf16 v[18:21], v[134:137], v[194:197], v[18:21]
	v_mfma_f32_16x16x32_bf16 v[14:17], v[142:145], v[194:197], v[14:17]
	v_mfma_f32_16x16x32_bf16 v[66:69], v[138:141], v[170:173], v[66:69]
	v_mfma_f32_16x16x32_bf16 v[62:65], v[146:149], v[170:173], v[62:65]
	v_mfma_f32_16x16x32_bf16 v[50:53], v[138:141], v[178:181], v[50:53]
	v_mfma_f32_16x16x32_bf16 v[46:49], v[146:149], v[178:181], v[46:49]
	v_mfma_f32_16x16x32_bf16 v[34:37], v[138:141], v[190:193], v[34:37]
	v_mfma_f32_16x16x32_bf16 v[30:33], v[146:149], v[190:193], v[30:33]
	v_mfma_f32_16x16x32_bf16 v[18:21], v[138:141], v[228:231], v[18:21]
	v_mfma_f32_16x16x32_bf16 v[14:17], v[146:149], v[228:231], v[14:17]
	v_mfma_f32_16x16x32_bf16 v[58:61], v[150:153], v[166:169], v[58:61]
	v_mfma_f32_16x16x32_bf16 v[54:57], v[158:161], v[166:169], v[54:57]
	v_mfma_f32_16x16x32_bf16 v[42:45], v[150:153], v[174:177], v[42:45]
	v_mfma_f32_16x16x32_bf16 v[38:41], v[158:161], v[174:177], v[38:41]
	v_mfma_f32_16x16x32_bf16 v[26:29], v[150:153], v[186:189], v[26:29]
	v_mfma_f32_16x16x32_bf16 v[22:25], v[158:161], v[186:189], v[22:25]
	v_mfma_f32_16x16x32_bf16 v[10:13], v[150:153], v[194:197], v[10:13]
	v_mfma_f32_16x16x32_bf16 v[4:7], v[158:161], v[194:197], v[6:9]
	v_mfma_f32_16x16x32_bf16 v[58:61], v[154:157], v[170:173], v[58:61]
	v_mfma_f32_16x16x32_bf16 v[54:57], v[162:165], v[170:173], v[54:57]
	v_mfma_f32_16x16x32_bf16 v[42:45], v[154:157], v[178:181], v[42:45]
	v_mfma_f32_16x16x32_bf16 v[38:41], v[162:165], v[178:181], v[38:41]
	v_mfma_f32_16x16x32_bf16 v[26:29], v[154:157], v[190:193], v[26:29]
	v_mfma_f32_16x16x32_bf16 v[22:25], v[162:165], v[190:193], v[22:25]
	v_mfma_f32_16x16x32_bf16 v[10:13], v[154:157], v[228:231], v[10:13]
	v_mfma_f32_16x16x32_bf16 v[4:7], v[162:165], v[228:231], v[4:7]
	s_barrier
	s_setprio 0
	s_add_i32 s54, 0, 0x18000
	v_add_u32_e32 v3, s54, v221
	s_add_i32 s55, 0, 0x1c000
	ds_read_b128 v[134:137], v3
	ds_read_b128 v[138:141], v3 offset:1024
	ds_read_b128 v[142:145], v3 offset:2048
	ds_read_b128 v[146:149], v3 offset:3072
	v_add_u32_e32 v3, s55, v221
	ds_read_b128 v[150:153], v3
	ds_read_b128 v[154:157], v3 offset:1024
	ds_read_b128 v[158:161], v3 offset:2048
	ds_read_b128 v[162:165], v3 offset:3072
	s_add_u32 s52, s70, 0x4000
	s_addc_u32 s53, s71, 0
	s_mov_b32 m0, s77
	v_lshl_add_u64 v[8:9], s[52:53], 0, v[198:199]
	ds_read_b128 v[166:169], v225 offset:32768
	ds_read_b128 v[170:173], v225 offset:33792
	ds_read_b128 v[174:177], v225 offset:34816
	ds_read_b128 v[178:181], v225 offset:35840
	ds_read_b128 v[186:189], v225 offset:36864
	ds_read_b128 v[190:193], v225 offset:37888
	ds_read_b128 v[194:197], v225 offset:38912
	ds_read_b128 v[228:231], v225 offset:39936
	global_load_lds_dwordx4 v[8:9], off
	v_lshl_add_u64 v[8:9], s[52:53], 0, v[202:203]
	s_mov_b32 m0, s78
	s_nop 0
	global_load_lds_dwordx4 v[8:9], off
	s_waitcnt vmcnt(8)
	s_waitcnt lgkmcnt(0)
	s_setprio 1
	s_barrier
	v_mfma_f32_16x16x32_bf16 v[130:133], v[134:137], v[166:169], v[130:133]
	v_mfma_f32_16x16x32_bf16 v[126:129], v[142:145], v[166:169], v[126:129]
	v_mfma_f32_16x16x32_bf16 v[114:117], v[134:137], v[174:177], v[114:117]
	v_mfma_f32_16x16x32_bf16 v[110:113], v[142:145], v[174:177], v[110:113]
	v_mfma_f32_16x16x32_bf16 v[98:101], v[134:137], v[186:189], v[98:101]
	v_mfma_f32_16x16x32_bf16 v[94:97], v[142:145], v[186:189], v[94:97]
	v_mfma_f32_16x16x32_bf16 v[82:85], v[134:137], v[194:197], v[82:85]
	v_mfma_f32_16x16x32_bf16 v[78:81], v[142:145], v[194:197], v[78:81]
	v_mfma_f32_16x16x32_bf16 v[130:133], v[138:141], v[170:173], v[130:133]
	v_mfma_f32_16x16x32_bf16 v[126:129], v[146:149], v[170:173], v[126:129]
	v_mfma_f32_16x16x32_bf16 v[114:117], v[138:141], v[178:181], v[114:117]
	v_mfma_f32_16x16x32_bf16 v[110:113], v[146:149], v[178:181], v[110:113]
	v_mfma_f32_16x16x32_bf16 v[98:101], v[138:141], v[190:193], v[98:101]
	v_mfma_f32_16x16x32_bf16 v[94:97], v[146:149], v[190:193], v[94:97]
	v_mfma_f32_16x16x32_bf16 v[82:85], v[138:141], v[228:231], v[82:85]
	v_mfma_f32_16x16x32_bf16 v[78:81], v[146:149], v[228:231], v[78:81]
	v_mfma_f32_16x16x32_bf16 v[122:125], v[150:153], v[166:169], v[122:125]
	v_mfma_f32_16x16x32_bf16 v[118:121], v[158:161], v[166:169], v[118:121]
	v_mfma_f32_16x16x32_bf16 v[106:109], v[150:153], v[174:177], v[106:109]
	v_mfma_f32_16x16x32_bf16 v[102:105], v[158:161], v[174:177], v[102:105]
	v_mfma_f32_16x16x32_bf16 v[90:93], v[150:153], v[186:189], v[90:93]
	v_mfma_f32_16x16x32_bf16 v[86:89], v[158:161], v[186:189], v[86:89]
	v_mfma_f32_16x16x32_bf16 v[74:77], v[150:153], v[194:197], v[74:77]
	v_mfma_f32_16x16x32_bf16 v[70:73], v[158:161], v[194:197], v[70:73]
	v_mfma_f32_16x16x32_bf16 v[122:125], v[154:157], v[170:173], v[122:125]
	v_mfma_f32_16x16x32_bf16 v[118:121], v[162:165], v[170:173], v[118:121]
	v_mfma_f32_16x16x32_bf16 v[106:109], v[154:157], v[178:181], v[106:109]
	v_mfma_f32_16x16x32_bf16 v[102:105], v[162:165], v[178:181], v[102:105]
	v_mfma_f32_16x16x32_bf16 v[90:93], v[154:157], v[190:193], v[90:93]
	v_mfma_f32_16x16x32_bf16 v[86:89], v[162:165], v[190:193], v[86:89]
	v_mfma_f32_16x16x32_bf16 v[74:77], v[154:157], v[228:231], v[74:77]
	v_mfma_f32_16x16x32_bf16 v[70:73], v[162:165], v[228:231], v[70:73]
	s_barrier
; #define PG8_STAGE(bufoff, gbase, voff) do { _Pragma("unroll") for (int _i = 0; _i < 2; ++_i) \
;         __builtin_amdgcn_global_load_lds((const unsigned*)((const char*)(gbase) + (voff)[_i]), (PG8_LAS unsigned*)(lds + (bufoff) + ldsw + _i * 8192), 16, 0, 0); } while (0)
; #define PG8_LDA(dst, b, h) do { _Pragma("unroll") for (int m = 0; m < 4; ++m) _Pragma("unroll") for (int k = 0; k < 2; ++k) dst[m][k] = *(const PG8_LAS bf16x8*)(lds + PG8_SA(b, h) + aoff + m * 2048 + k * 1024); } while (0)
; #define PG8_MMA(ai, bj, At, Bt) do { __builtin_amdgcn_s_setprio(1); _Pragma("unroll") for (int m = 0; m < 4; ++m) _Pragma("unroll") for (int n = 0; n < 2; ++n) _Pragma("unroll") for (int k = 0; k < 2; ++k) \
;         acc[ai][bj][m][n] = __builtin_amdgcn_mfma_f32_16x16x32_bf16(Bt[n][k], At[m][k], acc[ai][bj][m][n], 0, 0, 0); __builtin_amdgcn_s_setprio(0); } while (0)
; #define PG8_WAIT_V(n) asm volatile("s_waitcnt vmcnt(" #n ")" ::: "memory")
; #define PG8_WAIT_L(n) asm volatile("s_waitcnt lgkmcnt(" #n ")" ::: "memory")
; #define PG8_BAR __builtin_amdgcn_s_barrier()
; #define PG8_SCHED __builtin_amdgcn_sched_barrier(0)
; template <class Epi, class Sched, bool ALIGN_EPI = false, bool SP2 = false>
; __device__ __forceinline__ void gemm_phase(PG8_LAS unsigned char* lds, const Gemm g, const Sched& S, const Epi& E) {
;     ...
;         for (int t = 0; t < nt; t += 2) {
;     ...
;             PG8_LDA(At, 1, 1); PG8_STAGE(PG8_SB(1, 0), b3, voffB); PG8_STAGE(PG8_SB(1, 1), b3 + hstepB, voffB); PG8_STAGE(PG8_SA(1, 0), a3, voffA);
;             PG8_WAIT_V(8); PG8_WAIT_L(0); PG8_BAR; PG8_MMA(1, 0, At, B0); PG8_MMA(1, 1, At, B1); PG8_BAR; PG8_SCHED;
	s_setprio 0
	s_add_u32 s52, s50, 0x8000
	s_addc_u32 s53, s51, 0
	s_add_i32 s54, s54, s73
	v_lshl_add_u64 v[8:9], s[52:53], 0, v[200:201]
	s_mov_b32 m0, s54
	ds_read_b128 v[166:169], v225 offset:49152
	ds_read_b128 v[170:173], v225 offset:50176
	ds_read_b128 v[174:177], v225 offset:51200
	ds_read_b128 v[178:181], v225 offset:52224
	ds_read_b128 v[186:189], v225 offset:53248
	ds_read_b128 v[190:193], v225 offset:54272
	ds_read_b128 v[194:197], v225 offset:55296
	ds_read_b128 v[228:231], v225 offset:56320
	global_load_lds_dwordx4 v[8:9], off
	s_add_i32 m0, s54, 0x2000
	s_add_u32 s50, s50, 0x9000
	v_lshl_add_u64 v[8:9], s[52:53], 0, v[204:205]
	s_addc_u32 s51, s51, 0
	s_add_i32 s52, s55, s73
	global_load_lds_dwordx4 v[8:9], off
	v_lshl_add_u64 v[8:9], s[50:51], 0, v[200:201]
	s_mov_b32 m0, s52
	s_nop 0
	global_load_lds_dwordx4 v[8:9], off
	v_lshl_add_u64 v[8:9], s[50:51], 0, v[204:205]
	s_add_i32 m0, s52, 0x2000
	s_nop 0
	global_load_lds_dwordx4 v[8:9], off
	v_lshl_add_u64 v[8:9], s[48:49], 0, v[198:199]
	s_mov_b32 m0, s81
	s_nop 0
	global_load_lds_dwordx4 v[8:9], off
	v_lshl_add_u64 v[8:9], s[48:49], 0, v[202:203]
	s_mov_b32 m0, s82
	s_nop 0
	global_load_lds_dwordx4 v[8:9], off
	s_waitcnt vmcnt(8)
	s_waitcnt lgkmcnt(0)
	s_setprio 1
	s_barrier
	v_mfma_f32_16x16x32_bf16 v[66:69], v[134:137], v[166:169], v[66:69]
	v_mfma_f32_16x16x32_bf16 v[62:65], v[142:145], v[166:169], v[62:65]
	v_mfma_f32_16x16x32_bf16 v[50:53], v[134:137], v[174:177], v[50:53]
	v_mfma_f32_16x16x32_bf16 v[46:49], v[142:145], v[174:177], v[46:49]
	v_mfma_f32_16x16x32_bf16 v[34:37], v[134:137], v[186:189], v[34:37]
	v_mfma_f32_16x16x32_bf16 v[30:33], v[142:145], v[186:189], v[30:33]
	v_mfma_f32_16x16x32_bf16 v[18:21], v[134:137], v[194:197], v[18:21]
	v_mfma_f32_16x16x32_bf16 v[14:17], v[142:145], v[194:197], v[14:17]
	v_mfma_f32_16x16x32_bf16 v[66:69], v[138:141], v[170:173], v[66:69]
	v_mfma_f32_16x16x32_bf16 v[62:65], v[146:149], v[170:173], v[62:65]
	v_mfma_f32_16x16x32_bf16 v[50:53], v[138:141], v[178:181], v[50:53]
	v_mfma_f32_16x16x32_bf16 v[46:49], v[146:149], v[178:181], v[46:49]
	v_mfma_f32_16x16x32_bf16 v[34:37], v[138:141], v[190:193], v[34:37]
	v_mfma_f32_16x16x32_bf16 v[30:33], v[146:149], v[190:193], v[30:33]
	v_mfma_f32_16x16x32_bf16 v[18:21], v[138:141], v[228:231], v[18:21]
	v_mfma_f32_16x16x32_bf16 v[14:17], v[146:149], v[228:231], v[14:17]
	v_mfma_f32_16x16x32_bf16 v[58:61], v[150:153], v[166:169], v[58:61]
	v_mfma_f32_16x16x32_bf16 v[54:57], v[158:161], v[166:169], v[54:57]
	v_mfma_f32_16x16x32_bf16 v[42:45], v[150:153], v[174:177], v[42:45]
	v_mfma_f32_16x16x32_bf16 v[38:41], v[158:161], v[174:177], v[38:41]
	v_mfma_f32_16x16x32_bf16 v[26:29], v[150:153], v[186:189], v[26:29]
	v_mfma_f32_16x16x32_bf16 v[22:25], v[158:161], v[186:189], v[22:25]
	v_mfma_f32_16x16x32_bf16 v[8:11], v[150:153], v[194:197], v[10:13]
	v_mfma_f32_16x16x32_bf16 v[4:7], v[158:161], v[194:197], v[4:7]
	v_mfma_f32_16x16x32_bf16 v[58:61], v[154:157], v[170:173], v[58:61]
	v_mfma_f32_16x16x32_bf16 v[54:57], v[162:165], v[170:173], v[54:57]
	v_mfma_f32_16x16x32_bf16 v[42:45], v[154:157], v[178:181], v[42:45]
	v_mfma_f32_16x16x32_bf16 v[38:41], v[162:165], v[178:181], v[38:41]
	v_mfma_f32_16x16x32_bf16 v[26:29], v[154:157], v[190:193], v[26:29]
	v_mfma_f32_16x16x32_bf16 v[22:25], v[162:165], v[190:193], v[22:25]
	v_mfma_f32_16x16x32_bf16 v[10:13], v[154:157], v[228:231], v[8:11]
	v_mfma_f32_16x16x32_bf16 v[6:9], v[162:165], v[228:231], v[4:7]
	s_barrier
	s_setprio 0
	s_add_i32 s56, s56, 2
	s_add_u32 s46, s46, 0x10000
	s_addc_u32 s47, s47, 0
	s_cmp_gt_u32 s56, 13
	s_cbranch_scc1 .LBB0_383

; #define PG8_STAGE(bufoff, gbase, voff) do { _Pragma("unroll") for (int _i = 0; _i < 2; ++_i) \
;         __builtin_amdgcn_global_load_lds((const unsigned*)((const char*)(gbase) + (voff)[_i]), (PG8_LAS unsigned*)(lds + (bufoff) + ldsw + _i * 8192), 16, 0, 0); } while (0)
; #define PG8_LDA(dst, b, h) do { _Pragma("unroll") for (int m = 0; m < 4; ++m) _Pragma("unroll") for (int k = 0; k < 2; ++k) dst[m][k] = *(const PG8_LAS bf16x8*)(lds + PG8_SA(b, h) + aoff + m * 2048 + k * 1024); } while (0)
; #define PG8_LDB(dst, b, h) do { _Pragma("unroll") for (int n = 0; n < 2; ++n) _Pragma("unroll") for (int k = 0; k < 2; ++k) dst[n][k] = *(const PG8_LAS bf16x8*)(lds + PG8_SB(b, h) + boff + n * 2048 + k * 1024); } while (0)
; #define PG8_MMA(ai, bj, At, Bt) do { __builtin_amdgcn_s_setprio(1); _Pragma("unroll") for (int m = 0; m < 4; ++m) _Pragma("unroll") for (int n = 0; n < 2; ++n) _Pragma("unroll") for (int k = 0; k < 2; ++k) \
;         acc[ai][bj][m][n] = __builtin_amdgcn_mfma_f32_16x16x32_bf16(Bt[n][k], At[m][k], acc[ai][bj][m][n], 0, 0, 0); __builtin_amdgcn_s_setprio(0); } while (0)
; #define PG8_WAIT_V(n) asm volatile("s_waitcnt vmcnt(" #n ")" ::: "memory")
; #define PG8_WAIT_L(n) asm volatile("s_waitcnt lgkmcnt(" #n ")" ::: "memory")
; #define PG8_BAR __builtin_amdgcn_s_barrier()
; template <class Epi, class Sched, bool ALIGN_EPI = false, bool SP2 = false>
; __device__ __forceinline__ void gemm_phase(PG8_LAS unsigned char* lds, const Gemm g, const Sched& S, const Epi& E) {
;     ...
;             const char* a1 = cA + (size_t)(t + 1) * kstep;
;             const char* a2 = last ? nA : cA + (size_t)(t + 2) * kstep; const char* b2 = last ? nB : cB + (size_t)(t + 2) * kstep;
;             const char* a3 = a2 + kstep; const char* b3 = b2 + kstep;
;             if (last && has_next) S.a_ready(nxt);
;             if constexpr (SP2) {
;             PG8_LDB(B0, 0, 0); PG8_LDB(B1, 0, 1); PG8_SCHED; PG8_LDA(At, 0, 0); PG8_STAGE(PG8_SA(1, 1), a1 + hstep, voffA);
;             PG8_WAIT_V(8); PG8_WAIT_L(0); PG8_BAR; PG8_MMA(0, 0, At, B0); PG8_MMA(0, 1, At, B1); PG8_BAR; PG8_SCHED;
;             PG8_LDA(At, 0, 1); PG8_STAGE(PG8_SB(0, 0), b2, voffB); PG8_STAGE(PG8_SB(0, 1), b2 + hstepB, voffB); PG8_STAGE(PG8_SA(0, 0), a2, voffA);
;             PG8_WAIT_V(8); PG8_WAIT_L(0); PG8_BAR; PG8_MMA(1, 0, At, B0); PG8_MMA(1, 1, At, B1); PG8_BAR; PG8_SCHED;
.LBB0_477:
	ds_read_b128 v[130:133], v201
	ds_read_b128 v[134:137], v201 offset:1024
	ds_read_b128 v[138:141], v201 offset:2048
	ds_read_b128 v[142:145], v201 offset:3072
	ds_read_b128 v[146:149], v202
	ds_read_b128 v[150:153], v202 offset:1024
	ds_read_b128 v[154:157], v202 offset:2048
	ds_read_b128 v[158:161], v202 offset:3072
	s_add_u32 s68, s50, 0x4000
	s_addc_u32 s69, s51, 0
	s_cmp_eq_u32 s55, 12
	s_cselect_b32 s72, s47, s68
	s_cselect_b32 s73, s29, s69
	s_cselect_b32 s70, s52, s53
	s_cselect_b32 s71, s27, s54
	s_add_u32 s68, s72, 0x8000
	s_addc_u32 s69, s73, 0
	v_lshl_add_u64 v[196:197], s[50:51], 0, v[188:189]
	s_add_i32 m0, s1, 0xc000
	ds_read_b128 v[162:165], v203
	ds_read_b128 v[166:169], v203 offset:1024
	ds_read_b128 v[170:173], v203 offset:2048
	ds_read_b128 v[174:177], v203 offset:3072
	ds_read_b128 v[208:211], v203 offset:4096
	ds_read_b128 v[212:215], v203 offset:5120
	ds_read_b128 v[220:223], v203 offset:6144
	ds_read_b128 v[224:227], v203 offset:7168
	global_load_lds_dwordx4 v[196:197], off
	v_lshl_add_u64 v[196:197], s[50:51], 0, v[190:191]
	s_add_i32 m0, s1, 0xe000
	s_nop 0
	global_load_lds_dwordx4 v[196:197], off
	s_waitcnt vmcnt(8)
	s_waitcnt lgkmcnt(0)
	s_setprio 1
	s_barrier
	v_mfma_f32_16x16x32_bf16 v[126:129], v[130:133], v[162:165], v[126:129]
	v_mfma_f32_16x16x32_bf16 v[122:125], v[138:141], v[162:165], v[122:125]
	v_mfma_f32_16x16x32_bf16 v[110:113], v[130:133], v[170:173], v[110:113]
	v_mfma_f32_16x16x32_bf16 v[106:109], v[138:141], v[170:173], v[106:109]
	v_mfma_f32_16x16x32_bf16 v[94:97], v[130:133], v[208:211], v[94:97]
	v_mfma_f32_16x16x32_bf16 v[90:93], v[138:141], v[208:211], v[90:93]
	v_mfma_f32_16x16x32_bf16 v[78:81], v[130:133], v[220:223], v[78:81]
	v_mfma_f32_16x16x32_bf16 v[74:77], v[138:141], v[220:223], v[74:77]
	v_mfma_f32_16x16x32_bf16 v[126:129], v[134:137], v[166:169], v[126:129]
	v_mfma_f32_16x16x32_bf16 v[122:125], v[142:145], v[166:169], v[122:125]
	v_mfma_f32_16x16x32_bf16 v[110:113], v[134:137], v[174:177], v[110:113]
	v_mfma_f32_16x16x32_bf16 v[106:109], v[142:145], v[174:177], v[106:109]
	v_mfma_f32_16x16x32_bf16 v[94:97], v[134:137], v[212:215], v[94:97]
	v_mfma_f32_16x16x32_bf16 v[90:93], v[142:145], v[212:215], v[90:93]
	v_mfma_f32_16x16x32_bf16 v[78:81], v[134:137], v[224:227], v[78:81]
	v_mfma_f32_16x16x32_bf16 v[74:77], v[142:145], v[224:227], v[74:77]
	v_mfma_f32_16x16x32_bf16 v[118:121], v[146:149], v[162:165], v[118:121]
	v_mfma_f32_16x16x32_bf16 v[114:117], v[154:157], v[162:165], v[114:117]
	v_mfma_f32_16x16x32_bf16 v[102:105], v[146:149], v[170:173], v[102:105]
	v_mfma_f32_16x16x32_bf16 v[98:101], v[154:157], v[170:173], v[98:101]
	v_mfma_f32_16x16x32_bf16 v[86:89], v[146:149], v[208:211], v[86:89]
	v_mfma_f32_16x16x32_bf16 v[82:85], v[154:157], v[208:211], v[82:85]
	v_mfma_f32_16x16x32_bf16 v[70:73], v[146:149], v[220:223], v[70:73]
	v_mfma_f32_16x16x32_bf16 v[66:69], v[154:157], v[220:223], v[66:69]
	v_mfma_f32_16x16x32_bf16 v[118:121], v[150:153], v[166:169], v[118:121]
	v_mfma_f32_16x16x32_bf16 v[114:117], v[158:161], v[166:169], v[114:117]
	v_mfma_f32_16x16x32_bf16 v[102:105], v[150:153], v[174:177], v[102:105]
	v_mfma_f32_16x16x32_bf16 v[98:101], v[158:161], v[174:177], v[98:101]
	v_mfma_f32_16x16x32_bf16 v[86:89], v[150:153], v[212:215], v[86:89]
	v_mfma_f32_16x16x32_bf16 v[82:85], v[158:161], v[212:215], v[82:85]
	v_mfma_f32_16x16x32_bf16 v[70:73], v[150:153], v[224:227], v[70:73]
	v_mfma_f32_16x16x32_bf16 v[66:69], v[158:161], v[224:227], v[66:69]
	s_barrier
	s_setprio 0
	s_add_i32 s79, s77, s0
	v_lshl_add_u64 v[196:197], s[70:71], 0, v[180:181]
	s_mov_b32 m0, s79
	ds_read_b128 v[162:165], v203 offset:16384
	ds_read_b128 v[166:169], v203 offset:17408
	ds_read_b128 v[170:173], v203 offset:18432
	ds_read_b128 v[174:177], v203 offset:19456
	ds_read_b128 v[208:211], v203 offset:20480
	ds_read_b128 v[212:215], v203 offset:21504
	ds_read_b128 v[220:223], v203 offset:22528
	ds_read_b128 v[224:227], v203 offset:23552
	global_load_lds_dwordx4 v[196:197], off
	s_add_i32 m0, s79, 0x2000
	s_add_u32 s80, s70, 0x1000
	v_lshl_add_u64 v[196:197], s[70:71], 0, v[184:185]
	s_addc_u32 s81, s71, 0
	s_add_i32 s79, s78, s0
	global_load_lds_dwordx4 v[196:197], off
	v_lshl_add_u64 v[196:197], s[80:81], 0, v[180:181]
	s_mov_b32 m0, s79
	s_nop 0
	global_load_lds_dwordx4 v[196:197], off
	v_lshl_add_u64 v[196:197], s[80:81], 0, v[184:185]
	s_add_i32 m0, s79, 0x2000
	s_nop 0
	global_load_lds_dwordx4 v[196:197], off
	v_lshl_add_u64 v[196:197], s[72:73], 0, v[178:179]
	s_mov_b32 m0, s1
	s_nop 0
	global_load_lds_dwordx4 v[196:197], off
	v_lshl_add_u64 v[196:197], s[72:73], 0, v[182:183]
	s_mov_b32 m0, s49
	s_nop 0
	global_load_lds_dwordx4 v[196:197], off
	s_waitcnt vmcnt(8)
	s_waitcnt lgkmcnt(0)
	s_setprio 1
	s_barrier
; #define PG8_STAGE(bufoff, gbase, voff) do { _Pragma("unroll") for (int _i = 0; _i < 2; ++_i) \
;         __builtin_amdgcn_global_load_lds((const unsigned*)((const char*)(gbase) + (voff)[_i]), (PG8_LAS unsigned*)(lds + (bufoff) + ldsw + _i * 8192), 16, 0, 0); } while (0)
; #define PG8_LDA(dst, b, h) do { _Pragma("unroll") for (int m = 0; m < 4; ++m) _Pragma("unroll") for (int k = 0; k < 2; ++k) dst[m][k] = *(const PG8_LAS bf16x8*)(lds + PG8_SA(b, h) + aoff + m * 2048 + k * 1024); } while (0)
; #define PG8_LDB(dst, b, h) do { _Pragma("unroll") for (int n = 0; n < 2; ++n) _Pragma("unroll") for (int k = 0; k < 2; ++k) dst[n][k] = *(const PG8_LAS bf16x8*)(lds + PG8_SB(b, h) + boff + n * 2048 + k * 1024); } while (0)
; #define PG8_MMA(ai, bj, At, Bt) do { __builtin_amdgcn_s_setprio(1); _Pragma("unroll") for (int m = 0; m < 4; ++m) _Pragma("unroll") for (int n = 0; n < 2; ++n) _Pragma("unroll") for (int k = 0; k < 2; ++k) \
;         acc[ai][bj][m][n] = __builtin_amdgcn_mfma_f32_16x16x32_bf16(Bt[n][k], At[m][k], acc[ai][bj][m][n], 0, 0, 0); __builtin_amdgcn_s_setprio(0); } while (0)
; #define PG8_WAIT_V(n) asm volatile("s_waitcnt vmcnt(" #n ")" ::: "memory")
; #define PG8_WAIT_L(n) asm volatile("s_waitcnt lgkmcnt(" #n ")" ::: "memory")
; #define PG8_BAR __builtin_amdgcn_s_barrier()
; #define PG8_SCHED __builtin_amdgcn_sched_barrier(0)
; template <class Epi, class Sched, bool ALIGN_EPI = false, bool SP2 = false>
; __device__ __forceinline__ void gemm_phase(PG8_LAS unsigned char* lds, const Gemm g, const Sched& S, const Epi& E) {
;     ...
;             PG8_WAIT_V(8); PG8_WAIT_L(0); PG8_BAR; PG8_MMA(1, 0, At, B0); PG8_MMA(1, 1, At, B1); PG8_BAR; PG8_SCHED;
;             PG8_LDB(B0, 1, 0); PG8_LDB(B1, 1, 1); PG8_SCHED; PG8_LDA(At, 1, 0); PG8_STAGE(PG8_SA(0, 1), a2 + hstep, voffA);
;             PG8_WAIT_V(8); PG8_WAIT_L(0); PG8_BAR; PG8_MMA(0, 0, At, B0); PG8_MMA(0, 1, At, B1); PG8_BAR; PG8_SCHED;
	v_mfma_f32_16x16x32_bf16 v[62:65], v[130:133], v[162:165], v[62:65]
	v_mfma_f32_16x16x32_bf16 v[58:61], v[138:141], v[162:165], v[58:61]
	v_mfma_f32_16x16x32_bf16 v[46:49], v[130:133], v[170:173], v[46:49]
	v_mfma_f32_16x16x32_bf16 v[42:45], v[138:141], v[170:173], v[42:45]
	v_mfma_f32_16x16x32_bf16 v[30:33], v[130:133], v[208:211], v[30:33]
	v_mfma_f32_16x16x32_bf16 v[26:29], v[138:141], v[208:211], v[26:29]
	v_mfma_f32_16x16x32_bf16 v[14:17], v[130:133], v[220:223], v[14:17]
	v_mfma_f32_16x16x32_bf16 v[10:13], v[138:141], v[220:223], v[10:13]
	v_mfma_f32_16x16x32_bf16 v[62:65], v[134:137], v[166:169], v[62:65]
	v_mfma_f32_16x16x32_bf16 v[58:61], v[142:145], v[166:169], v[58:61]
	v_mfma_f32_16x16x32_bf16 v[46:49], v[134:137], v[174:177], v[46:49]
	v_mfma_f32_16x16x32_bf16 v[42:45], v[142:145], v[174:177], v[42:45]
	v_mfma_f32_16x16x32_bf16 v[30:33], v[134:137], v[212:215], v[30:33]
	v_mfma_f32_16x16x32_bf16 v[26:29], v[142:145], v[212:215], v[26:29]
	v_mfma_f32_16x16x32_bf16 v[14:17], v[134:137], v[224:227], v[14:17]
	v_mfma_f32_16x16x32_bf16 v[10:13], v[142:145], v[224:227], v[10:13]
	v_mfma_f32_16x16x32_bf16 v[54:57], v[146:149], v[162:165], v[54:57]
	v_mfma_f32_16x16x32_bf16 v[50:53], v[154:157], v[162:165], v[50:53]
	v_mfma_f32_16x16x32_bf16 v[38:41], v[146:149], v[170:173], v[38:41]
	v_mfma_f32_16x16x32_bf16 v[34:37], v[154:157], v[170:173], v[34:37]
	v_mfma_f32_16x16x32_bf16 v[22:25], v[146:149], v[208:211], v[22:25]
	v_mfma_f32_16x16x32_bf16 v[18:21], v[154:157], v[208:211], v[18:21]
	v_mfma_f32_16x16x32_bf16 v[6:9], v[146:149], v[220:223], v[6:9]
	v_mfma_f32_16x16x32_bf16 v[2:5], v[154:157], v[220:223], v[2:5]
	v_mfma_f32_16x16x32_bf16 v[54:57], v[150:153], v[166:169], v[54:57]
	v_mfma_f32_16x16x32_bf16 v[50:53], v[158:161], v[166:169], v[50:53]
	v_mfma_f32_16x16x32_bf16 v[38:41], v[150:153], v[174:177], v[38:41]
	v_mfma_f32_16x16x32_bf16 v[34:37], v[158:161], v[174:177], v[34:37]
	v_mfma_f32_16x16x32_bf16 v[22:25], v[150:153], v[212:215], v[22:25]
	v_mfma_f32_16x16x32_bf16 v[18:21], v[158:161], v[212:215], v[18:21]
	v_mfma_f32_16x16x32_bf16 v[6:9], v[150:153], v[224:227], v[6:9]
	v_mfma_f32_16x16x32_bf16 v[2:5], v[158:161], v[224:227], v[2:5]
	s_barrier
	s_setprio 0
	s_add_i32 s79, 0, 0x18000
	s_add_i32 s80, 0, 0x1c000
	v_add_u32_e32 v142, s79, v199
	v_add_u32_e32 v158, s80, v199
	ds_read_b128 v[130:133], v142
	ds_read_b128 v[134:137], v142 offset:1024
	ds_read_b128 v[138:141], v142 offset:2048
	ds_read_b128 v[142:145], v142 offset:3072
	ds_read_b128 v[146:149], v158
	ds_read_b128 v[150:153], v158 offset:1024
	ds_read_b128 v[154:157], v158 offset:2048
	ds_read_b128 v[158:161], v158 offset:3072
	s_add_u32 s72, s72, 0x4000
	s_addc_u32 s73, s73, 0
	s_mov_b32 m0, s56
	v_lshl_add_u64 v[196:197], s[72:73], 0, v[178:179]
	ds_read_b128 v[162:165], v203 offset:32768
	ds_read_b128 v[166:169], v203 offset:33792
	ds_read_b128 v[170:173], v203 offset:34816
	ds_read_b128 v[174:177], v203 offset:35840
	ds_read_b128 v[208:211], v203 offset:36864
	ds_read_b128 v[212:215], v203 offset:37888
	ds_read_b128 v[220:223], v203 offset:38912
	ds_read_b128 v[224:227], v203 offset:39936
	global_load_lds_dwordx4 v[196:197], off
	v_lshl_add_u64 v[196:197], s[72:73], 0, v[182:183]
	s_mov_b32 m0, s57
	s_nop 0
	global_load_lds_dwordx4 v[196:197], off
	s_waitcnt vmcnt(8)
	s_waitcnt lgkmcnt(0)
	s_setprio 1
	s_barrier
	v_mfma_f32_16x16x32_bf16 v[126:129], v[130:133], v[162:165], v[126:129]
	v_mfma_f32_16x16x32_bf16 v[122:125], v[138:141], v[162:165], v[122:125]
	v_mfma_f32_16x16x32_bf16 v[110:113], v[130:133], v[170:173], v[110:113]
	v_mfma_f32_16x16x32_bf16 v[106:109], v[138:141], v[170:173], v[106:109]
	v_mfma_f32_16x16x32_bf16 v[94:97], v[130:133], v[208:211], v[94:97]
	v_mfma_f32_16x16x32_bf16 v[90:93], v[138:141], v[208:211], v[90:93]
	v_mfma_f32_16x16x32_bf16 v[78:81], v[130:133], v[220:223], v[78:81]
	v_mfma_f32_16x16x32_bf16 v[74:77], v[138:141], v[220:223], v[74:77]
	v_mfma_f32_16x16x32_bf16 v[126:129], v[134:137], v[166:169], v[126:129]
	v_mfma_f32_16x16x32_bf16 v[122:125], v[142:145], v[166:169], v[122:125]
	v_mfma_f32_16x16x32_bf16 v[110:113], v[134:137], v[174:177], v[110:113]
	v_mfma_f32_16x16x32_bf16 v[106:109], v[142:145], v[174:177], v[106:109]
	v_mfma_f32_16x16x32_bf16 v[94:97], v[134:137], v[212:215], v[94:97]
	v_mfma_f32_16x16x32_bf16 v[90:93], v[142:145], v[212:215], v[90:93]
	v_mfma_f32_16x16x32_bf16 v[78:81], v[134:137], v[224:227], v[78:81]
	v_mfma_f32_16x16x32_bf16 v[74:77], v[142:145], v[224:227], v[74:77]
	v_mfma_f32_16x16x32_bf16 v[118:121], v[146:149], v[162:165], v[118:121]
	v_mfma_f32_16x16x32_bf16 v[114:117], v[154:157], v[162:165], v[114:117]
	v_mfma_f32_16x16x32_bf16 v[102:105], v[146:149], v[170:173], v[102:105]
	v_mfma_f32_16x16x32_bf16 v[98:101], v[154:157], v[170:173], v[98:101]
	v_mfma_f32_16x16x32_bf16 v[86:89], v[146:149], v[208:211], v[86:89]
	v_mfma_f32_16x16x32_bf16 v[82:85], v[154:157], v[208:211], v[82:85]
	v_mfma_f32_16x16x32_bf16 v[70:73], v[146:149], v[220:223], v[70:73]
	v_mfma_f32_16x16x32_bf16 v[66:69], v[154:157], v[220:223], v[66:69]
	v_mfma_f32_16x16x32_bf16 v[118:121], v[150:153], v[166:169], v[118:121]
	v_mfma_f32_16x16x32_bf16 v[114:117], v[158:161], v[166:169], v[114:117]
	v_mfma_f32_16x16x32_bf16 v[102:105], v[150:153], v[174:177], v[102:105]
	v_mfma_f32_16x16x32_bf16 v[98:101], v[158:161], v[174:177], v[98:101]
	v_mfma_f32_16x16x32_bf16 v[86:89], v[150:153], v[212:215], v[86:89]
	v_mfma_f32_16x16x32_bf16 v[82:85], v[158:161], v[212:215], v[82:85]
	v_mfma_f32_16x16x32_bf16 v[70:73], v[150:153], v[224:227], v[70:73]
	v_mfma_f32_16x16x32_bf16 v[66:69], v[158:161], v[224:227], v[66:69]
	s_barrier
; #define PG8_STAGE(bufoff, gbase, voff) do { _Pragma("unroll") for (int _i = 0; _i < 2; ++_i) \
;         __builtin_amdgcn_global_load_lds((const unsigned*)((const char*)(gbase) + (voff)[_i]), (PG8_LAS unsigned*)(lds + (bufoff) + ldsw + _i * 8192), 16, 0, 0); } while (0)
; #define PG8_LDA(dst, b, h) do { _Pragma("unroll") for (int m = 0; m < 4; ++m) _Pragma("unroll") for (int k = 0; k < 2; ++k) dst[m][k] = *(const PG8_LAS bf16x8*)(lds + PG8_SA(b, h) + aoff + m * 2048 + k * 1024); } while (0)
; #define PG8_MMA(ai, bj, At, Bt) do { __builtin_amdgcn_s_setprio(1); _Pragma("unroll") for (int m = 0; m < 4; ++m) _Pragma("unroll") for (int n = 0; n < 2; ++n) _Pragma("unroll") for (int k = 0; k < 2; ++k) \
;         acc[ai][bj][m][n] = __builtin_amdgcn_mfma_f32_16x16x32_bf16(Bt[n][k], At[m][k], acc[ai][bj][m][n], 0, 0, 0); __builtin_amdgcn_s_setprio(0); } while (0)
; #define PG8_WAIT_V(n) asm volatile("s_waitcnt vmcnt(" #n ")" ::: "memory")
; #define PG8_WAIT_L(n) asm volatile("s_waitcnt lgkmcnt(" #n ")" ::: "memory")
; #define PG8_BAR __builtin_amdgcn_s_barrier()
; #define PG8_SCHED __builtin_amdgcn_sched_barrier(0)
; template <class Epi, class Sched, bool ALIGN_EPI = false, bool SP2 = false>
; __device__ __forceinline__ void gemm_phase(PG8_LAS unsigned char* lds, const Gemm g, const Sched& S, const Epi& E) {
;     ...
;             PG8_LDA(At, 1, 1); PG8_STAGE(PG8_SB(1, 0), b3, voffB); PG8_STAGE(PG8_SB(1, 1), b3 + hstepB, voffB); PG8_STAGE(PG8_SA(1, 0), a3, voffA);
;             PG8_WAIT_V(8); PG8_WAIT_L(0); PG8_BAR; PG8_MMA(1, 0, At, B0); PG8_MMA(1, 1, At, B1); PG8_BAR; PG8_SCHED;
;     ...
;         if constexpr (ALIGN_EPI) { if (wr == 0) PG8_BAR; }
	s_setprio 0
	s_add_u32 s72, s70, 0x8000
	s_addc_u32 s73, s71, 0
	s_add_i32 s79, s79, s0
	v_lshl_add_u64 v[196:197], s[72:73], 0, v[180:181]
	s_mov_b32 m0, s79
	ds_read_b128 v[162:165], v203 offset:49152
	ds_read_b128 v[166:169], v203 offset:50176
	ds_read_b128 v[170:173], v203 offset:51200
	ds_read_b128 v[174:177], v203 offset:52224
	ds_read_b128 v[208:211], v203 offset:53248
	ds_read_b128 v[212:215], v203 offset:54272
	ds_read_b128 v[220:223], v203 offset:55296
	ds_read_b128 v[224:227], v203 offset:56320
	global_load_lds_dwordx4 v[196:197], off
	s_add_i32 m0, s79, 0x2000
	s_add_u32 s70, s70, 0x9000
	v_lshl_add_u64 v[196:197], s[72:73], 0, v[184:185]
	s_addc_u32 s71, s71, 0
	s_add_i32 s72, s80, s0
	global_load_lds_dwordx4 v[196:197], off
	v_lshl_add_u64 v[196:197], s[70:71], 0, v[180:181]
	s_mov_b32 m0, s72
	s_nop 0
	global_load_lds_dwordx4 v[196:197], off
	v_lshl_add_u64 v[196:197], s[70:71], 0, v[184:185]
	s_add_i32 m0, s72, 0x2000
	s_nop 0
	global_load_lds_dwordx4 v[196:197], off
	v_lshl_add_u64 v[196:197], s[68:69], 0, v[178:179]
	s_mov_b32 m0, s59
	s_nop 0
	global_load_lds_dwordx4 v[196:197], off
	v_lshl_add_u64 v[196:197], s[68:69], 0, v[182:183]
	s_mov_b32 m0, s74
	s_nop 0
	global_load_lds_dwordx4 v[196:197], off
	s_waitcnt vmcnt(8)
	s_waitcnt lgkmcnt(0)
	s_setprio 1
	s_barrier
	v_mfma_f32_16x16x32_bf16 v[62:65], v[130:133], v[162:165], v[62:65]
	v_mfma_f32_16x16x32_bf16 v[58:61], v[138:141], v[162:165], v[58:61]
	v_mfma_f32_16x16x32_bf16 v[46:49], v[130:133], v[170:173], v[46:49]
	v_mfma_f32_16x16x32_bf16 v[42:45], v[138:141], v[170:173], v[42:45]
	v_mfma_f32_16x16x32_bf16 v[30:33], v[130:133], v[208:211], v[30:33]
	v_mfma_f32_16x16x32_bf16 v[26:29], v[138:141], v[208:211], v[26:29]
	v_mfma_f32_16x16x32_bf16 v[14:17], v[130:133], v[220:223], v[14:17]
	v_mfma_f32_16x16x32_bf16 v[10:13], v[138:141], v[220:223], v[10:13]
	v_mfma_f32_16x16x32_bf16 v[62:65], v[134:137], v[166:169], v[62:65]
	v_mfma_f32_16x16x32_bf16 v[58:61], v[142:145], v[166:169], v[58:61]
	v_mfma_f32_16x16x32_bf16 v[46:49], v[134:137], v[174:177], v[46:49]
	v_mfma_f32_16x16x32_bf16 v[42:45], v[142:145], v[174:177], v[42:45]
	v_mfma_f32_16x16x32_bf16 v[30:33], v[134:137], v[212:215], v[30:33]
	v_mfma_f32_16x16x32_bf16 v[26:29], v[142:145], v[212:215], v[26:29]
	v_mfma_f32_16x16x32_bf16 v[14:17], v[134:137], v[224:227], v[14:17]
	v_mfma_f32_16x16x32_bf16 v[10:13], v[142:145], v[224:227], v[10:13]
	v_mfma_f32_16x16x32_bf16 v[54:57], v[146:149], v[162:165], v[54:57]
	v_mfma_f32_16x16x32_bf16 v[50:53], v[154:157], v[162:165], v[50:53]
	v_mfma_f32_16x16x32_bf16 v[38:41], v[146:149], v[170:173], v[38:41]
	v_mfma_f32_16x16x32_bf16 v[34:37], v[154:157], v[170:173], v[34:37]
	v_mfma_f32_16x16x32_bf16 v[22:25], v[146:149], v[208:211], v[22:25]
	v_mfma_f32_16x16x32_bf16 v[18:21], v[154:157], v[208:211], v[18:21]
	v_mfma_f32_16x16x32_bf16 v[6:9], v[146:149], v[220:223], v[6:9]
	v_mfma_f32_16x16x32_bf16 v[2:5], v[154:157], v[220:223], v[2:5]
	v_mfma_f32_16x16x32_bf16 v[54:57], v[150:153], v[166:169], v[54:57]
	v_mfma_f32_16x16x32_bf16 v[50:53], v[158:161], v[166:169], v[50:53]
	v_mfma_f32_16x16x32_bf16 v[38:41], v[150:153], v[174:177], v[38:41]
	v_mfma_f32_16x16x32_bf16 v[34:37], v[158:161], v[174:177], v[34:37]
	v_mfma_f32_16x16x32_bf16 v[22:25], v[150:153], v[212:215], v[22:25]
	v_mfma_f32_16x16x32_bf16 v[18:21], v[158:161], v[212:215], v[18:21]
	v_mfma_f32_16x16x32_bf16 v[6:9], v[150:153], v[224:227], v[6:9]
	v_mfma_f32_16x16x32_bf16 v[2:5], v[158:161], v[224:227], v[2:5]
	s_barrier
	s_setprio 0
	s_add_i32 s55, s55, 2
	s_add_u32 s50, s50, 0x10000
	s_addc_u32 s51, s51, 0
	s_add_u32 s53, s53, 0x10000
	s_addc_u32 s54, s54, 0
	s_cmp_gt_u32 s55, 13
	s_cbranch_scc0 .LBB0_477
	s_and_b64 vcc, exec, s[14:15]
	s_cbranch_vccz .LBB0_480
	s_barrier

; #define PG8_STAGE(bufoff, gbase, voff) do { _Pragma("unroll") for (int _i = 0; _i < 2; ++_i) \
;         __builtin_amdgcn_global_load_lds((const unsigned*)((const char*)(gbase) + (voff)[_i]), (PG8_LAS unsigned*)(lds + (bufoff) + ldsw + _i * 8192), 16, 0, 0); } while (0)
; #define PG8_LDA(dst, b, h) do { _Pragma("unroll") for (int m = 0; m < 4; ++m) _Pragma("unroll") for (int k = 0; k < 2; ++k) dst[m][k] = *(const PG8_LAS bf16x8*)(lds + PG8_SA(b, h) + aoff + m * 2048 + k * 1024); } while (0)
; #define PG8_LDB(dst, b, h) do { _Pragma("unroll") for (int n = 0; n < 2; ++n) _Pragma("unroll") for (int k = 0; k < 2; ++k) dst[n][k] = *(const PG8_LAS bf16x8*)(lds + PG8_SB(b, h) + boff + n * 2048 + k * 1024); } while (0)
; #define PG8_MMA(ai, bj, At, Bt) do { __builtin_amdgcn_s_setprio(1); _Pragma("unroll") for (int m = 0; m < 4; ++m) _Pragma("unroll") for (int n = 0; n < 2; ++n) _Pragma("unroll") for (int k = 0; k < 2; ++k) \
;         acc[ai][bj][m][n] = __builtin_amdgcn_mfma_f32_16x16x32_bf16(Bt[n][k], At[m][k], acc[ai][bj][m][n], 0, 0, 0); __builtin_amdgcn_s_setprio(0); } while (0)
; #define PG8_WAIT_V(n) asm volatile("s_waitcnt vmcnt(" #n ")" ::: "memory")
; #define PG8_WAIT_L(n) asm volatile("s_waitcnt lgkmcnt(" #n ")" ::: "memory")
; #define PG8_BAR __builtin_amdgcn_s_barrier()
; template <class Epi, class Sched, bool ALIGN_EPI = false, bool SP2 = false>
; __device__ __forceinline__ void gemm_phase(PG8_LAS unsigned char* lds, const Gemm g, const Sched& S, const Epi& E) {
;     ...
;             const char* a1 = cA + (size_t)(t + 1) * kstep;
;             const char* a2 = last ? nA : cA + (size_t)(t + 2) * kstep; const char* b2 = last ? nB : cB + (size_t)(t + 2) * kstep;
;             const char* a3 = a2 + kstep; const char* b3 = b2 + kstep;
;             if (last && has_next) S.a_ready(nxt);
;             if constexpr (SP2) {
;             PG8_LDB(B0, 0, 0); PG8_LDB(B1, 0, 1); PG8_SCHED; PG8_LDA(At, 0, 0); PG8_STAGE(PG8_SA(1, 1), a1 + hstep, voffA);
;             PG8_WAIT_V(8); PG8_WAIT_L(0); PG8_BAR; PG8_MMA(0, 0, At, B0); PG8_MMA(0, 1, At, B1); PG8_BAR; PG8_SCHED;
;             PG8_LDA(At, 0, 1); PG8_STAGE(PG8_SB(0, 0), b2, voffB); PG8_STAGE(PG8_SB(0, 1), b2 + hstepB, voffB); PG8_STAGE(PG8_SA(0, 0), a2, voffA);
;             PG8_WAIT_V(8); PG8_WAIT_L(0); PG8_BAR; PG8_MMA(1, 0, At, B0); PG8_MMA(1, 1, At, B1); PG8_BAR; PG8_SCHED;
.LBB0_586:
	ds_read_b128 v[166:169], v153
	ds_read_b128 v[170:173], v153 offset:1024
	ds_read_b128 v[174:177], v153 offset:2048
	ds_read_b128 v[178:181], v153 offset:3072
	ds_read_b128 v[182:185], v154
	ds_read_b128 v[186:189], v154 offset:1024
	ds_read_b128 v[190:193], v154 offset:2048
	ds_read_b128 v[194:197], v154 offset:3072
	s_add_u32 s28, s26, 0x4000
	s_addc_u32 s29, s27, 0
	s_cmp_eq_u32 s59, 12
	s_cselect_b32 s42, s55, s28
	s_cselect_b32 s43, s19, s29
	s_cselect_b32 s36, s56, s57
	s_cselect_b32 s37, s17, s58
	s_add_u32 s28, s42, 0x8000
	s_addc_u32 s29, s43, 0
	v_lshl_add_u64 v[232:233], s[26:27], 0, v[142:143]
	s_add_i32 m0, s3, 0xc000
	ds_read_b128 v[198:201], v155
	ds_read_b128 v[202:205], v155 offset:1024
	ds_read_b128 v[206:209], v155 offset:2048
	ds_read_b128 v[210:213], v155 offset:3072
	ds_read_b128 v[214:217], v155 offset:4096
	ds_read_b128 v[220:223], v155 offset:5120
	ds_read_b128 v[224:227], v155 offset:6144
	ds_read_b128 v[228:231], v155 offset:7168
	global_load_lds_dwordx4 v[232:233], off
	v_lshl_add_u64 v[232:233], s[26:27], 0, v[144:145]
	s_add_i32 m0, s3, 0xe000
	s_nop 0
	global_load_lds_dwordx4 v[232:233], off
	s_waitcnt vmcnt(8)
	s_waitcnt lgkmcnt(0)
	s_setprio 1
	s_barrier
	v_mfma_f32_16x16x32_bf16 v[126:129], v[166:169], v[198:201], v[126:129]
	v_mfma_f32_16x16x32_bf16 v[122:125], v[174:177], v[198:201], v[122:125]
	v_mfma_f32_16x16x32_bf16 v[110:113], v[166:169], v[206:209], v[110:113]
	v_mfma_f32_16x16x32_bf16 v[106:109], v[174:177], v[206:209], v[106:109]
	v_mfma_f32_16x16x32_bf16 v[94:97], v[166:169], v[214:217], v[94:97]
	v_mfma_f32_16x16x32_bf16 v[90:93], v[174:177], v[214:217], v[90:93]
	v_mfma_f32_16x16x32_bf16 v[78:81], v[166:169], v[224:227], v[78:81]
	v_mfma_f32_16x16x32_bf16 v[74:77], v[174:177], v[224:227], v[74:77]
	v_mfma_f32_16x16x32_bf16 v[126:129], v[170:173], v[202:205], v[126:129]
	v_mfma_f32_16x16x32_bf16 v[122:125], v[178:181], v[202:205], v[122:125]
	v_mfma_f32_16x16x32_bf16 v[110:113], v[170:173], v[210:213], v[110:113]
	v_mfma_f32_16x16x32_bf16 v[106:109], v[178:181], v[210:213], v[106:109]
	v_mfma_f32_16x16x32_bf16 v[94:97], v[170:173], v[220:223], v[94:97]
	v_mfma_f32_16x16x32_bf16 v[90:93], v[178:181], v[220:223], v[90:93]
	v_mfma_f32_16x16x32_bf16 v[78:81], v[170:173], v[228:231], v[78:81]
	v_mfma_f32_16x16x32_bf16 v[74:77], v[178:181], v[228:231], v[74:77]
	v_mfma_f32_16x16x32_bf16 v[118:121], v[182:185], v[198:201], v[118:121]
	v_mfma_f32_16x16x32_bf16 v[114:117], v[190:193], v[198:201], v[114:117]
	v_mfma_f32_16x16x32_bf16 v[102:105], v[182:185], v[206:209], v[102:105]
	v_mfma_f32_16x16x32_bf16 v[98:101], v[190:193], v[206:209], v[98:101]
	v_mfma_f32_16x16x32_bf16 v[86:89], v[182:185], v[214:217], v[86:89]
	v_mfma_f32_16x16x32_bf16 v[82:85], v[190:193], v[214:217], v[82:85]
	v_mfma_f32_16x16x32_bf16 v[70:73], v[182:185], v[224:227], v[70:73]
	v_mfma_f32_16x16x32_bf16 v[66:69], v[190:193], v[224:227], v[66:69]
	v_mfma_f32_16x16x32_bf16 v[118:121], v[186:189], v[202:205], v[118:121]
	v_mfma_f32_16x16x32_bf16 v[114:117], v[194:197], v[202:205], v[114:117]
	v_mfma_f32_16x16x32_bf16 v[102:105], v[186:189], v[210:213], v[102:105]
	v_mfma_f32_16x16x32_bf16 v[98:101], v[194:197], v[210:213], v[98:101]
	v_mfma_f32_16x16x32_bf16 v[86:89], v[186:189], v[220:223], v[86:89]
	v_mfma_f32_16x16x32_bf16 v[82:85], v[194:197], v[220:223], v[82:85]
	v_mfma_f32_16x16x32_bf16 v[70:73], v[186:189], v[228:231], v[70:73]
	v_mfma_f32_16x16x32_bf16 v[66:69], v[194:197], v[228:231], v[66:69]
	s_barrier
	s_setprio 0
	s_add_i32 s66, s8, s1
	v_lshl_add_u64 v[232:233], s[36:37], 0, v[132:133]
	s_mov_b32 m0, s66
	ds_read_b128 v[198:201], v155 offset:16384
	ds_read_b128 v[202:205], v155 offset:17408
	ds_read_b128 v[206:209], v155 offset:18432
	ds_read_b128 v[210:213], v155 offset:19456
	ds_read_b128 v[214:217], v155 offset:20480
	ds_read_b128 v[220:223], v155 offset:21504
	ds_read_b128 v[224:227], v155 offset:22528
	ds_read_b128 v[228:231], v155 offset:23552
	global_load_lds_dwordx4 v[232:233], off
	s_add_i32 m0, s66, 0x2000
	s_add_u32 s66, s36, 0x1000
	v_lshl_add_u64 v[232:233], s[36:37], 0, v[136:137]
	s_addc_u32 s67, s37, 0
	s_add_i32 s68, s52, s1
	global_load_lds_dwordx4 v[232:233], off
	v_lshl_add_u64 v[232:233], s[66:67], 0, v[132:133]
	s_mov_b32 m0, s68
	s_nop 0
	global_load_lds_dwordx4 v[232:233], off
	v_lshl_add_u64 v[232:233], s[66:67], 0, v[136:137]
	s_add_i32 m0, s68, 0x2000
	s_nop 0
	global_load_lds_dwordx4 v[232:233], off
	v_lshl_add_u64 v[232:233], s[42:43], 0, v[130:131]
	s_mov_b32 m0, s3
	s_nop 0
	global_load_lds_dwordx4 v[232:233], off
	v_lshl_add_u64 v[232:233], s[42:43], 0, v[134:135]
	s_mov_b32 m0, s44
	s_nop 0
	global_load_lds_dwordx4 v[232:233], off
	s_waitcnt vmcnt(8)
	s_waitcnt lgkmcnt(0)
	s_setprio 1
	s_barrier
; #define PG8_STAGE(bufoff, gbase, voff) do { _Pragma("unroll") for (int _i = 0; _i < 2; ++_i) \
;         __builtin_amdgcn_global_load_lds((const unsigned*)((const char*)(gbase) + (voff)[_i]), (PG8_LAS unsigned*)(lds + (bufoff) + ldsw + _i * 8192), 16, 0, 0); } while (0)
; #define PG8_LDA(dst, b, h) do { _Pragma("unroll") for (int m = 0; m < 4; ++m) _Pragma("unroll") for (int k = 0; k < 2; ++k) dst[m][k] = *(const PG8_LAS bf16x8*)(lds + PG8_SA(b, h) + aoff + m * 2048 + k * 1024); } while (0)
; #define PG8_LDB(dst, b, h) do { _Pragma("unroll") for (int n = 0; n < 2; ++n) _Pragma("unroll") for (int k = 0; k < 2; ++k) dst[n][k] = *(const PG8_LAS bf16x8*)(lds + PG8_SB(b, h) + boff + n * 2048 + k * 1024); } while (0)
; #define PG8_MMA(ai, bj, At, Bt) do { __builtin_amdgcn_s_setprio(1); _Pragma("unroll") for (int m = 0; m < 4; ++m) _Pragma("unroll") for (int n = 0; n < 2; ++n) _Pragma("unroll") for (int k = 0; k < 2; ++k) \
;         acc[ai][bj][m][n] = __builtin_amdgcn_mfma_f32_16x16x32_bf16(Bt[n][k], At[m][k], acc[ai][bj][m][n], 0, 0, 0); __builtin_amdgcn_s_setprio(0); } while (0)
; #define PG8_WAIT_V(n) asm volatile("s_waitcnt vmcnt(" #n ")" ::: "memory")
; #define PG8_WAIT_L(n) asm volatile("s_waitcnt lgkmcnt(" #n ")" ::: "memory")
; #define PG8_BAR __builtin_amdgcn_s_barrier()
; #define PG8_SCHED __builtin_amdgcn_sched_barrier(0)
; template <class Epi, class Sched, bool ALIGN_EPI = false, bool SP2 = false>
; __device__ __forceinline__ void gemm_phase(PG8_LAS unsigned char* lds, const Gemm g, const Sched& S, const Epi& E) {
;     ...
;             PG8_WAIT_V(8); PG8_WAIT_L(0); PG8_BAR; PG8_MMA(1, 0, At, B0); PG8_MMA(1, 1, At, B1); PG8_BAR; PG8_SCHED;
;             PG8_LDB(B0, 1, 0); PG8_LDB(B1, 1, 1); PG8_SCHED; PG8_LDA(At, 1, 0); PG8_STAGE(PG8_SA(0, 1), a2 + hstep, voffA);
;             PG8_WAIT_V(8); PG8_WAIT_L(0); PG8_BAR; PG8_MMA(0, 0, At, B0); PG8_MMA(0, 1, At, B1); PG8_BAR; PG8_SCHED;
	v_mfma_f32_16x16x32_bf16 v[62:65], v[166:169], v[198:201], v[62:65]
	v_mfma_f32_16x16x32_bf16 v[58:61], v[174:177], v[198:201], v[58:61]
	v_mfma_f32_16x16x32_bf16 v[46:49], v[166:169], v[206:209], v[46:49]
	v_mfma_f32_16x16x32_bf16 v[42:45], v[174:177], v[206:209], v[42:45]
	v_mfma_f32_16x16x32_bf16 v[30:33], v[166:169], v[214:217], v[30:33]
	v_mfma_f32_16x16x32_bf16 v[26:29], v[174:177], v[214:217], v[26:29]
	v_mfma_f32_16x16x32_bf16 v[14:17], v[166:169], v[224:227], v[14:17]
	v_mfma_f32_16x16x32_bf16 v[10:13], v[174:177], v[224:227], v[10:13]
	v_mfma_f32_16x16x32_bf16 v[62:65], v[170:173], v[202:205], v[62:65]
	v_mfma_f32_16x16x32_bf16 v[58:61], v[178:181], v[202:205], v[58:61]
	v_mfma_f32_16x16x32_bf16 v[46:49], v[170:173], v[210:213], v[46:49]
	v_mfma_f32_16x16x32_bf16 v[42:45], v[178:181], v[210:213], v[42:45]
	v_mfma_f32_16x16x32_bf16 v[30:33], v[170:173], v[220:223], v[30:33]
	v_mfma_f32_16x16x32_bf16 v[26:29], v[178:181], v[220:223], v[26:29]
	v_mfma_f32_16x16x32_bf16 v[14:17], v[170:173], v[228:231], v[14:17]
	v_mfma_f32_16x16x32_bf16 v[10:13], v[178:181], v[228:231], v[10:13]
	v_mfma_f32_16x16x32_bf16 v[54:57], v[182:185], v[198:201], v[54:57]
	v_mfma_f32_16x16x32_bf16 v[50:53], v[190:193], v[198:201], v[50:53]
	v_mfma_f32_16x16x32_bf16 v[38:41], v[182:185], v[206:209], v[38:41]
	v_mfma_f32_16x16x32_bf16 v[34:37], v[190:193], v[206:209], v[34:37]
	v_mfma_f32_16x16x32_bf16 v[22:25], v[182:185], v[214:217], v[22:25]
	v_mfma_f32_16x16x32_bf16 v[18:21], v[190:193], v[214:217], v[18:21]
	v_mfma_f32_16x16x32_bf16 v[6:9], v[182:185], v[224:227], v[6:9]
	v_mfma_f32_16x16x32_bf16 v[2:5], v[190:193], v[224:227], v[2:5]
	v_mfma_f32_16x16x32_bf16 v[54:57], v[186:189], v[202:205], v[54:57]
	v_mfma_f32_16x16x32_bf16 v[50:53], v[194:197], v[202:205], v[50:53]
	v_mfma_f32_16x16x32_bf16 v[38:41], v[186:189], v[210:213], v[38:41]
	v_mfma_f32_16x16x32_bf16 v[34:37], v[194:197], v[210:213], v[34:37]
	v_mfma_f32_16x16x32_bf16 v[22:25], v[186:189], v[220:223], v[22:25]
	v_mfma_f32_16x16x32_bf16 v[18:21], v[194:197], v[220:223], v[18:21]
	v_mfma_f32_16x16x32_bf16 v[6:9], v[186:189], v[228:231], v[6:9]
	v_mfma_f32_16x16x32_bf16 v[2:5], v[194:197], v[228:231], v[2:5]
	s_barrier
	s_setprio 0
	s_add_i32 s66, 0, 0x18000
	v_add_u32_e32 v165, s66, v151
	s_add_i32 s67, 0, 0x1c000
	ds_read_b128 v[166:169], v165
	ds_read_b128 v[170:173], v165 offset:1024
	ds_read_b128 v[174:177], v165 offset:2048
	ds_read_b128 v[178:181], v165 offset:3072
	v_add_u32_e32 v165, s67, v151
	ds_read_b128 v[182:185], v165
	ds_read_b128 v[186:189], v165 offset:1024
	ds_read_b128 v[190:193], v165 offset:2048
	ds_read_b128 v[194:197], v165 offset:3072
	s_add_u32 s42, s42, 0x4000
	s_addc_u32 s43, s43, 0
	s_mov_b32 m0, s45
	v_lshl_add_u64 v[232:233], s[42:43], 0, v[130:131]
	ds_read_b128 v[198:201], v155 offset:32768
	ds_read_b128 v[202:205], v155 offset:33792
	ds_read_b128 v[206:209], v155 offset:34816
	ds_read_b128 v[210:213], v155 offset:35840
	ds_read_b128 v[214:217], v155 offset:36864
	ds_read_b128 v[220:223], v155 offset:37888
	ds_read_b128 v[224:227], v155 offset:38912
	ds_read_b128 v[228:231], v155 offset:39936
	global_load_lds_dwordx4 v[232:233], off
	v_lshl_add_u64 v[232:233], s[42:43], 0, v[134:135]
	s_mov_b32 m0, s46
	s_nop 0
	global_load_lds_dwordx4 v[232:233], off
	s_waitcnt vmcnt(8)
	s_waitcnt lgkmcnt(0)
	s_setprio 1
	s_barrier
	v_mfma_f32_16x16x32_bf16 v[126:129], v[166:169], v[198:201], v[126:129]
	v_mfma_f32_16x16x32_bf16 v[122:125], v[174:177], v[198:201], v[122:125]
	v_mfma_f32_16x16x32_bf16 v[110:113], v[166:169], v[206:209], v[110:113]
	v_mfma_f32_16x16x32_bf16 v[106:109], v[174:177], v[206:209], v[106:109]
	v_mfma_f32_16x16x32_bf16 v[94:97], v[166:169], v[214:217], v[94:97]
	v_mfma_f32_16x16x32_bf16 v[90:93], v[174:177], v[214:217], v[90:93]
	v_mfma_f32_16x16x32_bf16 v[78:81], v[166:169], v[224:227], v[78:81]
	v_mfma_f32_16x16x32_bf16 v[74:77], v[174:177], v[224:227], v[74:77]
	v_mfma_f32_16x16x32_bf16 v[126:129], v[170:173], v[202:205], v[126:129]
	v_mfma_f32_16x16x32_bf16 v[122:125], v[178:181], v[202:205], v[122:125]
	v_mfma_f32_16x16x32_bf16 v[110:113], v[170:173], v[210:213], v[110:113]
	v_mfma_f32_16x16x32_bf16 v[106:109], v[178:181], v[210:213], v[106:109]
	v_mfma_f32_16x16x32_bf16 v[94:97], v[170:173], v[220:223], v[94:97]
	v_mfma_f32_16x16x32_bf16 v[90:93], v[178:181], v[220:223], v[90:93]
	v_mfma_f32_16x16x32_bf16 v[78:81], v[170:173], v[228:231], v[78:81]
	v_mfma_f32_16x16x32_bf16 v[74:77], v[178:181], v[228:231], v[74:77]
	v_mfma_f32_16x16x32_bf16 v[118:121], v[182:185], v[198:201], v[118:121]
	v_mfma_f32_16x16x32_bf16 v[114:117], v[190:193], v[198:201], v[114:117]
	v_mfma_f32_16x16x32_bf16 v[102:105], v[182:185], v[206:209], v[102:105]
	v_mfma_f32_16x16x32_bf16 v[98:101], v[190:193], v[206:209], v[98:101]
	v_mfma_f32_16x16x32_bf16 v[86:89], v[182:185], v[214:217], v[86:89]
	v_mfma_f32_16x16x32_bf16 v[82:85], v[190:193], v[214:217], v[82:85]
	v_mfma_f32_16x16x32_bf16 v[70:73], v[182:185], v[224:227], v[70:73]
	v_mfma_f32_16x16x32_bf16 v[66:69], v[190:193], v[224:227], v[66:69]
	v_mfma_f32_16x16x32_bf16 v[118:121], v[186:189], v[202:205], v[118:121]
	v_mfma_f32_16x16x32_bf16 v[114:117], v[194:197], v[202:205], v[114:117]
	v_mfma_f32_16x16x32_bf16 v[102:105], v[186:189], v[210:213], v[102:105]
	v_mfma_f32_16x16x32_bf16 v[98:101], v[194:197], v[210:213], v[98:101]
	v_mfma_f32_16x16x32_bf16 v[86:89], v[186:189], v[220:223], v[86:89]
	v_mfma_f32_16x16x32_bf16 v[82:85], v[194:197], v[220:223], v[82:85]
	v_mfma_f32_16x16x32_bf16 v[70:73], v[186:189], v[228:231], v[70:73]
	v_mfma_f32_16x16x32_bf16 v[66:69], v[194:197], v[228:231], v[66:69]
	s_barrier
; #define PG8_STAGE(bufoff, gbase, voff) do { _Pragma("unroll") for (int _i = 0; _i < 2; ++_i) \
;         __builtin_amdgcn_global_load_lds((const unsigned*)((const char*)(gbase) + (voff)[_i]), (PG8_LAS unsigned*)(lds + (bufoff) + ldsw + _i * 8192), 16, 0, 0); } while (0)
; #define PG8_LDA(dst, b, h) do { _Pragma("unroll") for (int m = 0; m < 4; ++m) _Pragma("unroll") for (int k = 0; k < 2; ++k) dst[m][k] = *(const PG8_LAS bf16x8*)(lds + PG8_SA(b, h) + aoff + m * 2048 + k * 1024); } while (0)
; #define PG8_MMA(ai, bj, At, Bt) do { __builtin_amdgcn_s_setprio(1); _Pragma("unroll") for (int m = 0; m < 4; ++m) _Pragma("unroll") for (int n = 0; n < 2; ++n) _Pragma("unroll") for (int k = 0; k < 2; ++k) \
;         acc[ai][bj][m][n] = __builtin_amdgcn_mfma_f32_16x16x32_bf16(Bt[n][k], At[m][k], acc[ai][bj][m][n], 0, 0, 0); __builtin_amdgcn_s_setprio(0); } while (0)
; #define PG8_WAIT_V(n) asm volatile("s_waitcnt vmcnt(" #n ")" ::: "memory")
; #define PG8_WAIT_L(n) asm volatile("s_waitcnt lgkmcnt(" #n ")" ::: "memory")
; #define PG8_BAR __builtin_amdgcn_s_barrier()
; #define PG8_SCHED __builtin_amdgcn_sched_barrier(0)
; template <class Epi, class Sched, bool ALIGN_EPI = false, bool SP2 = false>
; __device__ __forceinline__ void gemm_phase(PG8_LAS unsigned char* lds, const Gemm g, const Sched& S, const Epi& E) {
;     ...
;             PG8_LDA(At, 1, 1); PG8_STAGE(PG8_SB(1, 0), b3, voffB); PG8_STAGE(PG8_SB(1, 1), b3 + hstepB, voffB); PG8_STAGE(PG8_SA(1, 0), a3, voffA);
;             PG8_WAIT_V(8); PG8_WAIT_L(0); PG8_BAR; PG8_MMA(1, 0, At, B0); PG8_MMA(1, 1, At, B1); PG8_BAR; PG8_SCHED;
;     ...
;         if constexpr (ALIGN_EPI) { if (wr == 0) PG8_BAR; }
	s_setprio 0
	s_add_u32 s42, s36, 0x8000
	s_addc_u32 s43, s37, 0
	s_add_i32 s66, s66, s1
	v_lshl_add_u64 v[232:233], s[42:43], 0, v[132:133]
	s_mov_b32 m0, s66
	ds_read_b128 v[198:201], v155 offset:49152
	ds_read_b128 v[202:205], v155 offset:50176
	ds_read_b128 v[206:209], v155 offset:51200
	ds_read_b128 v[210:213], v155 offset:52224
	ds_read_b128 v[214:217], v155 offset:53248
	ds_read_b128 v[220:223], v155 offset:54272
	ds_read_b128 v[224:227], v155 offset:55296
	ds_read_b128 v[228:231], v155 offset:56320
	global_load_lds_dwordx4 v[232:233], off
	s_add_i32 m0, s66, 0x2000
	s_add_u32 s36, s36, 0x9000
	v_lshl_add_u64 v[232:233], s[42:43], 0, v[136:137]
	s_addc_u32 s37, s37, 0
	s_add_i32 s42, s67, s1
	global_load_lds_dwordx4 v[232:233], off
	v_lshl_add_u64 v[232:233], s[36:37], 0, v[132:133]
	s_mov_b32 m0, s42
	s_nop 0
	global_load_lds_dwordx4 v[232:233], off
	v_lshl_add_u64 v[232:233], s[36:37], 0, v[136:137]
	s_add_i32 m0, s42, 0x2000
	s_nop 0
	global_load_lds_dwordx4 v[232:233], off
	v_lshl_add_u64 v[232:233], s[28:29], 0, v[130:131]
	s_mov_b32 m0, s49
	s_nop 0
	global_load_lds_dwordx4 v[232:233], off
	v_lshl_add_u64 v[232:233], s[28:29], 0, v[134:135]
	s_mov_b32 m0, s50
	s_nop 0
	global_load_lds_dwordx4 v[232:233], off
	s_waitcnt vmcnt(8)
	s_waitcnt lgkmcnt(0)
	s_setprio 1
	s_barrier
	v_mfma_f32_16x16x32_bf16 v[62:65], v[166:169], v[198:201], v[62:65]
	v_mfma_f32_16x16x32_bf16 v[58:61], v[174:177], v[198:201], v[58:61]
	v_mfma_f32_16x16x32_bf16 v[46:49], v[166:169], v[206:209], v[46:49]
	v_mfma_f32_16x16x32_bf16 v[42:45], v[174:177], v[206:209], v[42:45]
	v_mfma_f32_16x16x32_bf16 v[30:33], v[166:169], v[214:217], v[30:33]
	v_mfma_f32_16x16x32_bf16 v[26:29], v[174:177], v[214:217], v[26:29]
	v_mfma_f32_16x16x32_bf16 v[14:17], v[166:169], v[224:227], v[14:17]
	v_mfma_f32_16x16x32_bf16 v[10:13], v[174:177], v[224:227], v[10:13]
	v_mfma_f32_16x16x32_bf16 v[62:65], v[170:173], v[202:205], v[62:65]
	v_mfma_f32_16x16x32_bf16 v[58:61], v[178:181], v[202:205], v[58:61]
	v_mfma_f32_16x16x32_bf16 v[46:49], v[170:173], v[210:213], v[46:49]
	v_mfma_f32_16x16x32_bf16 v[42:45], v[178:181], v[210:213], v[42:45]
	v_mfma_f32_16x16x32_bf16 v[30:33], v[170:173], v[220:223], v[30:33]
	v_mfma_f32_16x16x32_bf16 v[26:29], v[178:181], v[220:223], v[26:29]
	v_mfma_f32_16x16x32_bf16 v[14:17], v[170:173], v[228:231], v[14:17]
	v_mfma_f32_16x16x32_bf16 v[10:13], v[178:181], v[228:231], v[10:13]
	v_mfma_f32_16x16x32_bf16 v[54:57], v[182:185], v[198:201], v[54:57]
	v_mfma_f32_16x16x32_bf16 v[50:53], v[190:193], v[198:201], v[50:53]
	v_mfma_f32_16x16x32_bf16 v[38:41], v[182:185], v[206:209], v[38:41]
	v_mfma_f32_16x16x32_bf16 v[34:37], v[190:193], v[206:209], v[34:37]
	v_mfma_f32_16x16x32_bf16 v[22:25], v[182:185], v[214:217], v[22:25]
	v_mfma_f32_16x16x32_bf16 v[18:21], v[190:193], v[214:217], v[18:21]
	v_mfma_f32_16x16x32_bf16 v[6:9], v[182:185], v[224:227], v[6:9]
	v_mfma_f32_16x16x32_bf16 v[2:5], v[190:193], v[224:227], v[2:5]
	v_mfma_f32_16x16x32_bf16 v[54:57], v[186:189], v[202:205], v[54:57]
	v_mfma_f32_16x16x32_bf16 v[50:53], v[194:197], v[202:205], v[50:53]
	v_mfma_f32_16x16x32_bf16 v[38:41], v[186:189], v[210:213], v[38:41]
	v_mfma_f32_16x16x32_bf16 v[34:37], v[194:197], v[210:213], v[34:37]
	v_mfma_f32_16x16x32_bf16 v[22:25], v[186:189], v[220:223], v[22:25]
	v_mfma_f32_16x16x32_bf16 v[18:21], v[194:197], v[220:223], v[18:21]
	v_mfma_f32_16x16x32_bf16 v[6:9], v[186:189], v[228:231], v[6:9]
	v_mfma_f32_16x16x32_bf16 v[2:5], v[194:197], v[228:231], v[2:5]
	s_barrier
	s_setprio 0
	s_add_i32 s59, s59, 2
	s_add_u32 s26, s26, 0x10000
	s_addc_u32 s27, s27, 0
	s_add_u32 s57, s57, 0x10000
	s_addc_u32 s58, s58, 0
	s_cmp_gt_u32 s59, 13
	s_cbranch_scc0 .LBB0_586
	s_and_b64 vcc, exec, s[12:13]
	s_cbranch_vccz .LBB0_589
	s_barrier

; #define PG8_STAGE(bufoff, gbase, voff) do { _Pragma("unroll") for (int _i = 0; _i < 2; ++_i) \
;         __builtin_amdgcn_global_load_lds((const unsigned*)((const char*)(gbase) + (voff)[_i]), (PG8_LAS unsigned*)(lds + (bufoff) + ldsw + _i * 8192), 16, 0, 0); } while (0)
; #define PG8_LDA(dst, b, h) do { _Pragma("unroll") for (int m = 0; m < 4; ++m) _Pragma("unroll") for (int k = 0; k < 2; ++k) dst[m][k] = *(const PG8_LAS bf16x8*)(lds + PG8_SA(b, h) + aoff + m * 2048 + k * 1024); } while (0)
; #define PG8_LDB(dst, b, h) do { _Pragma("unroll") for (int n = 0; n < 2; ++n) _Pragma("unroll") for (int k = 0; k < 2; ++k) dst[n][k] = *(const PG8_LAS bf16x8*)(lds + PG8_SB(b, h) + boff + n * 2048 + k * 1024); } while (0)
; #define PG8_MMA(ai, bj, At, Bt) do { __builtin_amdgcn_s_setprio(1); _Pragma("unroll") for (int m = 0; m < 4; ++m) _Pragma("unroll") for (int n = 0; n < 2; ++n) _Pragma("unroll") for (int k = 0; k < 2; ++k) \
;         acc[ai][bj][m][n] = __builtin_amdgcn_mfma_f32_16x16x32_bf16(Bt[n][k], At[m][k], acc[ai][bj][m][n], 0, 0, 0); __builtin_amdgcn_s_setprio(0); } while (0)
; #define PG8_WAIT_V(n) asm volatile("s_waitcnt vmcnt(" #n ")" ::: "memory")
; #define PG8_WAIT_L(n) asm volatile("s_waitcnt lgkmcnt(" #n ")" ::: "memory")
; #define PG8_BAR __builtin_amdgcn_s_barrier()
; template <class Epi, class Sched, bool ALIGN_EPI = false, bool SP2 = false>
; __device__ __forceinline__ void gemm_phase(PG8_LAS unsigned char* lds, const Gemm g, const Sched& S, const Epi& E) {
;     ...
;             const char* a1 = cA + (size_t)(t + 1) * kstep;
;             const char* a2 = last ? nA : cA + (size_t)(t + 2) * kstep; const char* b2 = last ? nB : cB + (size_t)(t + 2) * kstep;
;             const char* a3 = a2 + kstep; const char* b3 = b2 + kstep;
;             if (last && has_next) S.a_ready(nxt);
;             if constexpr (SP2) {
;             PG8_LDB(B0, 0, 0); PG8_LDB(B1, 0, 1); PG8_SCHED; PG8_LDA(At, 0, 0); PG8_STAGE(PG8_SA(1, 1), a1 + hstep, voffA);
;             PG8_WAIT_V(8); PG8_WAIT_L(0); PG8_BAR; PG8_MMA(0, 0, At, B0); PG8_MMA(0, 1, At, B1); PG8_BAR; PG8_SCHED;
;             PG8_LDA(At, 0, 1); PG8_STAGE(PG8_SB(0, 0), b2, voffB); PG8_STAGE(PG8_SB(0, 1), b2 + hstepB, voffB); PG8_STAGE(PG8_SA(0, 0), a2, voffA);
;             PG8_WAIT_V(8); PG8_WAIT_L(0); PG8_BAR; PG8_MMA(1, 0, At, B0); PG8_MMA(1, 1, At, B1); PG8_BAR; PG8_SCHED;
.LBB0_682:
	ds_read_b128 v[98:101], v215
	ds_read_b128 v[102:105], v215 offset:1024
	ds_read_b128 v[122:125], v215 offset:2048
	ds_read_b128 v[126:129], v215 offset:3072
	ds_read_b128 v[146:149], v216
	ds_read_b128 v[150:153], v216 offset:1024
	ds_read_b128 v[154:157], v216 offset:2048
	ds_read_b128 v[158:161], v216 offset:3072
	s_add_u32 s42, s36, 0x4000
	s_addc_u32 s43, s37, 0
	s_cmp_eq_u32 s54, 60
	s_cselect_b32 s46, s23, s42
	s_cselect_b32 s47, s9, s43
	s_cselect_b32 s44, s29, s52
	s_cselect_b32 s45, s21, s53
	s_add_u32 s42, s46, 0x8000
	s_addc_u32 s43, s47, 0
	v_lshl_add_u64 v[230:231], s[36:37], 0, v[198:199]
	s_add_i32 m0, s1, 0xc000
	ds_read_b128 v[162:165], v217
	ds_read_b128 v[166:169], v217 offset:1024
	ds_read_b128 v[170:173], v217 offset:2048
	ds_read_b128 v[174:177], v217 offset:3072
	ds_read_b128 v[178:181], v217 offset:4096
	ds_read_b128 v[182:185], v217 offset:5120
	ds_read_b128 v[222:225], v217 offset:6144
	ds_read_b128 v[226:229], v217 offset:7168
	global_load_lds_dwordx4 v[230:231], off
	v_lshl_add_u64 v[230:231], s[36:37], 0, v[200:201]
	s_add_i32 m0, s1, 0xe000
	s_nop 0
	global_load_lds_dwordx4 v[230:231], off
	s_waitcnt vmcnt(8)
	s_waitcnt lgkmcnt(0)
	s_setprio 1
	s_barrier
	v_mfma_f32_16x16x32_bf16 v[142:145], v[98:101], v[162:165], v[142:145]
	v_mfma_f32_16x16x32_bf16 v[138:141], v[122:125], v[162:165], v[138:141]
	v_mfma_f32_16x16x32_bf16 v[118:121], v[98:101], v[170:173], v[118:121]
	v_mfma_f32_16x16x32_bf16 v[114:117], v[122:125], v[170:173], v[114:117]
	v_mfma_f32_16x16x32_bf16 v[94:97], v[98:101], v[178:181], v[94:97]
	v_mfma_f32_16x16x32_bf16 v[90:93], v[122:125], v[178:181], v[90:93]
	v_mfma_f32_16x16x32_bf16 v[78:81], v[98:101], v[222:225], v[78:81]
	v_mfma_f32_16x16x32_bf16 v[74:77], v[122:125], v[222:225], v[74:77]
	v_mfma_f32_16x16x32_bf16 v[142:145], v[102:105], v[166:169], v[142:145]
	v_mfma_f32_16x16x32_bf16 v[138:141], v[126:129], v[166:169], v[138:141]
	v_mfma_f32_16x16x32_bf16 v[118:121], v[102:105], v[174:177], v[118:121]
	v_mfma_f32_16x16x32_bf16 v[114:117], v[126:129], v[174:177], v[114:117]
	v_mfma_f32_16x16x32_bf16 v[94:97], v[102:105], v[182:185], v[94:97]
	v_mfma_f32_16x16x32_bf16 v[90:93], v[126:129], v[182:185], v[90:93]
	v_mfma_f32_16x16x32_bf16 v[78:81], v[102:105], v[226:229], v[78:81]
	v_mfma_f32_16x16x32_bf16 v[74:77], v[126:129], v[226:229], v[74:77]
	v_mfma_f32_16x16x32_bf16 v[134:137], v[146:149], v[162:165], v[134:137]
	v_mfma_f32_16x16x32_bf16 v[130:133], v[154:157], v[162:165], v[130:133]
	v_mfma_f32_16x16x32_bf16 v[110:113], v[146:149], v[170:173], v[110:113]
	v_mfma_f32_16x16x32_bf16 v[106:109], v[154:157], v[170:173], v[106:109]
	v_mfma_f32_16x16x32_bf16 v[86:89], v[146:149], v[178:181], v[86:89]
	v_mfma_f32_16x16x32_bf16 v[82:85], v[154:157], v[178:181], v[82:85]
	v_mfma_f32_16x16x32_bf16 v[70:73], v[146:149], v[222:225], v[70:73]
	v_mfma_f32_16x16x32_bf16 v[66:69], v[154:157], v[222:225], v[66:69]
	v_mfma_f32_16x16x32_bf16 v[134:137], v[150:153], v[166:169], v[134:137]
	v_mfma_f32_16x16x32_bf16 v[130:133], v[158:161], v[166:169], v[130:133]
	v_mfma_f32_16x16x32_bf16 v[110:113], v[150:153], v[174:177], v[110:113]
	v_mfma_f32_16x16x32_bf16 v[106:109], v[158:161], v[174:177], v[106:109]
	v_mfma_f32_16x16x32_bf16 v[86:89], v[150:153], v[182:185], v[86:89]
	v_mfma_f32_16x16x32_bf16 v[82:85], v[158:161], v[182:185], v[82:85]
	v_mfma_f32_16x16x32_bf16 v[70:73], v[150:153], v[226:229], v[70:73]
	v_mfma_f32_16x16x32_bf16 v[66:69], v[158:161], v[226:229], v[66:69]
	s_barrier
	s_setprio 0
	s_add_i32 s55, s59, s0
	v_lshl_add_u64 v[230:231], s[44:45], 0, v[188:189]
	s_mov_b32 m0, s55
	ds_read_b128 v[162:165], v217 offset:16384
	ds_read_b128 v[166:169], v217 offset:17408
	ds_read_b128 v[170:173], v217 offset:18432
	ds_read_b128 v[174:177], v217 offset:19456
	ds_read_b128 v[178:181], v217 offset:20480
	ds_read_b128 v[182:185], v217 offset:21504
	ds_read_b128 v[222:225], v217 offset:22528
	ds_read_b128 v[226:229], v217 offset:23552
	global_load_lds_dwordx4 v[230:231], off
	s_add_i32 m0, s55, 0x2000
	s_add_u32 s68, s44, 0x1000
	v_lshl_add_u64 v[230:231], s[44:45], 0, v[192:193]
	s_addc_u32 s69, s45, 0
	s_add_i32 s55, s64, s0
	global_load_lds_dwordx4 v[230:231], off
	v_lshl_add_u64 v[230:231], s[68:69], 0, v[188:189]
	s_mov_b32 m0, s55
	s_nop 0
	global_load_lds_dwordx4 v[230:231], off
	v_lshl_add_u64 v[230:231], s[68:69], 0, v[192:193]
	s_add_i32 m0, s55, 0x2000
	s_nop 0
	global_load_lds_dwordx4 v[230:231], off
	v_lshl_add_u64 v[230:231], s[46:47], 0, v[186:187]
	s_mov_b32 m0, s1
	s_nop 0
	global_load_lds_dwordx4 v[230:231], off
	v_lshl_add_u64 v[230:231], s[46:47], 0, v[190:191]
	s_mov_b32 m0, s3
	s_nop 0
	global_load_lds_dwordx4 v[230:231], off
	s_waitcnt vmcnt(8)
	s_waitcnt lgkmcnt(0)
	s_setprio 1
	s_barrier
; #define PG8_STAGE(bufoff, gbase, voff) do { _Pragma("unroll") for (int _i = 0; _i < 2; ++_i) \
;         __builtin_amdgcn_global_load_lds((const unsigned*)((const char*)(gbase) + (voff)[_i]), (PG8_LAS unsigned*)(lds + (bufoff) + ldsw + _i * 8192), 16, 0, 0); } while (0)
; #define PG8_LDA(dst, b, h) do { _Pragma("unroll") for (int m = 0; m < 4; ++m) _Pragma("unroll") for (int k = 0; k < 2; ++k) dst[m][k] = *(const PG8_LAS bf16x8*)(lds + PG8_SA(b, h) + aoff + m * 2048 + k * 1024); } while (0)
; #define PG8_LDB(dst, b, h) do { _Pragma("unroll") for (int n = 0; n < 2; ++n) _Pragma("unroll") for (int k = 0; k < 2; ++k) dst[n][k] = *(const PG8_LAS bf16x8*)(lds + PG8_SB(b, h) + boff + n * 2048 + k * 1024); } while (0)
; #define PG8_MMA(ai, bj, At, Bt) do { __builtin_amdgcn_s_setprio(1); _Pragma("unroll") for (int m = 0; m < 4; ++m) _Pragma("unroll") for (int n = 0; n < 2; ++n) _Pragma("unroll") for (int k = 0; k < 2; ++k) \
;         acc[ai][bj][m][n] = __builtin_amdgcn_mfma_f32_16x16x32_bf16(Bt[n][k], At[m][k], acc[ai][bj][m][n], 0, 0, 0); __builtin_amdgcn_s_setprio(0); } while (0)
; #define PG8_WAIT_V(n) asm volatile("s_waitcnt vmcnt(" #n ")" ::: "memory")
; #define PG8_WAIT_L(n) asm volatile("s_waitcnt lgkmcnt(" #n ")" ::: "memory")
; #define PG8_BAR __builtin_amdgcn_s_barrier()
; #define PG8_SCHED __builtin_amdgcn_sched_barrier(0)
; template <class Epi, class Sched, bool ALIGN_EPI = false, bool SP2 = false>
; __device__ __forceinline__ void gemm_phase(PG8_LAS unsigned char* lds, const Gemm g, const Sched& S, const Epi& E) {
;     ...
;             PG8_WAIT_V(8); PG8_WAIT_L(0); PG8_BAR; PG8_MMA(1, 0, At, B0); PG8_MMA(1, 1, At, B1); PG8_BAR; PG8_SCHED;
;             PG8_LDB(B0, 1, 0); PG8_LDB(B1, 1, 1); PG8_SCHED; PG8_LDA(At, 1, 0); PG8_STAGE(PG8_SA(0, 1), a2 + hstep, voffA);
;             PG8_WAIT_V(8); PG8_WAIT_L(0); PG8_BAR; PG8_MMA(0, 0, At, B0); PG8_MMA(0, 1, At, B1); PG8_BAR; PG8_SCHED;
	v_mfma_f32_16x16x32_bf16 v[62:65], v[98:101], v[162:165], v[62:65]
	v_mfma_f32_16x16x32_bf16 v[58:61], v[122:125], v[162:165], v[58:61]
	v_mfma_f32_16x16x32_bf16 v[46:49], v[98:101], v[170:173], v[46:49]
	v_mfma_f32_16x16x32_bf16 v[42:45], v[122:125], v[170:173], v[42:45]
	v_mfma_f32_16x16x32_bf16 v[30:33], v[98:101], v[178:181], v[30:33]
	v_mfma_f32_16x16x32_bf16 v[26:29], v[122:125], v[178:181], v[26:29]
	v_mfma_f32_16x16x32_bf16 v[14:17], v[98:101], v[222:225], v[14:17]
	v_mfma_f32_16x16x32_bf16 v[10:13], v[122:125], v[222:225], v[10:13]
	v_mfma_f32_16x16x32_bf16 v[62:65], v[102:105], v[166:169], v[62:65]
	v_mfma_f32_16x16x32_bf16 v[58:61], v[126:129], v[166:169], v[58:61]
	v_mfma_f32_16x16x32_bf16 v[46:49], v[102:105], v[174:177], v[46:49]
	v_mfma_f32_16x16x32_bf16 v[42:45], v[126:129], v[174:177], v[42:45]
	v_mfma_f32_16x16x32_bf16 v[30:33], v[102:105], v[182:185], v[30:33]
	v_mfma_f32_16x16x32_bf16 v[26:29], v[126:129], v[182:185], v[26:29]
	v_mfma_f32_16x16x32_bf16 v[14:17], v[102:105], v[226:229], v[14:17]
	v_mfma_f32_16x16x32_bf16 v[10:13], v[126:129], v[226:229], v[10:13]
	v_mfma_f32_16x16x32_bf16 v[54:57], v[146:149], v[162:165], v[54:57]
	v_mfma_f32_16x16x32_bf16 v[50:53], v[154:157], v[162:165], v[50:53]
	v_mfma_f32_16x16x32_bf16 v[38:41], v[146:149], v[170:173], v[38:41]
	v_mfma_f32_16x16x32_bf16 v[34:37], v[154:157], v[170:173], v[34:37]
	v_mfma_f32_16x16x32_bf16 v[22:25], v[146:149], v[178:181], v[22:25]
	v_mfma_f32_16x16x32_bf16 v[18:21], v[154:157], v[178:181], v[18:21]
	v_mfma_f32_16x16x32_bf16 v[6:9], v[146:149], v[222:225], v[6:9]
	v_mfma_f32_16x16x32_bf16 v[2:5], v[154:157], v[222:225], v[2:5]
	v_mfma_f32_16x16x32_bf16 v[54:57], v[150:153], v[166:169], v[54:57]
	v_mfma_f32_16x16x32_bf16 v[50:53], v[158:161], v[166:169], v[50:53]
	v_mfma_f32_16x16x32_bf16 v[38:41], v[150:153], v[174:177], v[38:41]
	v_mfma_f32_16x16x32_bf16 v[34:37], v[158:161], v[174:177], v[34:37]
	v_mfma_f32_16x16x32_bf16 v[22:25], v[150:153], v[182:185], v[22:25]
	v_mfma_f32_16x16x32_bf16 v[18:21], v[158:161], v[182:185], v[18:21]
	v_mfma_f32_16x16x32_bf16 v[6:9], v[150:153], v[226:229], v[6:9]
	v_mfma_f32_16x16x32_bf16 v[2:5], v[158:161], v[226:229], v[2:5]
	s_barrier
	s_setprio 0
	s_add_i32 s55, 0, 0x18000
	s_add_i32 s67, 0, 0x1c000
	v_add_u32_e32 v126, s55, v214
	v_add_u32_e32 v158, s67, v214
	ds_read_b128 v[98:101], v126
	ds_read_b128 v[102:105], v126 offset:1024
	ds_read_b128 v[122:125], v126 offset:2048
	ds_read_b128 v[126:129], v126 offset:3072
	ds_read_b128 v[146:149], v158
	ds_read_b128 v[150:153], v158 offset:1024
	ds_read_b128 v[154:157], v158 offset:2048
	ds_read_b128 v[158:161], v158 offset:3072
	s_add_u32 s46, s46, 0x4000
	s_addc_u32 s47, s47, 0
	s_mov_b32 m0, s48
	v_lshl_add_u64 v[230:231], s[46:47], 0, v[186:187]
	ds_read_b128 v[162:165], v217 offset:32768
	ds_read_b128 v[166:169], v217 offset:33792
	ds_read_b128 v[170:173], v217 offset:34816
	ds_read_b128 v[174:177], v217 offset:35840
	ds_read_b128 v[178:181], v217 offset:36864
	ds_read_b128 v[182:185], v217 offset:37888
	ds_read_b128 v[222:225], v217 offset:38912
	ds_read_b128 v[226:229], v217 offset:39936
	global_load_lds_dwordx4 v[230:231], off
	v_lshl_add_u64 v[230:231], s[46:47], 0, v[190:191]
	s_mov_b32 m0, s49
	s_nop 0
	global_load_lds_dwordx4 v[230:231], off
	s_waitcnt vmcnt(8)
	s_waitcnt lgkmcnt(0)
	s_setprio 1
	s_barrier
	v_mfma_f32_16x16x32_bf16 v[142:145], v[98:101], v[162:165], v[142:145]
	v_mfma_f32_16x16x32_bf16 v[138:141], v[122:125], v[162:165], v[138:141]
	v_mfma_f32_16x16x32_bf16 v[118:121], v[98:101], v[170:173], v[118:121]
	v_mfma_f32_16x16x32_bf16 v[114:117], v[122:125], v[170:173], v[114:117]
	v_mfma_f32_16x16x32_bf16 v[94:97], v[98:101], v[178:181], v[94:97]
	v_mfma_f32_16x16x32_bf16 v[90:93], v[122:125], v[178:181], v[90:93]
	v_mfma_f32_16x16x32_bf16 v[78:81], v[98:101], v[222:225], v[78:81]
	v_mfma_f32_16x16x32_bf16 v[74:77], v[122:125], v[222:225], v[74:77]
	v_mfma_f32_16x16x32_bf16 v[142:145], v[102:105], v[166:169], v[142:145]
	v_mfma_f32_16x16x32_bf16 v[138:141], v[126:129], v[166:169], v[138:141]
	v_mfma_f32_16x16x32_bf16 v[118:121], v[102:105], v[174:177], v[118:121]
	v_mfma_f32_16x16x32_bf16 v[114:117], v[126:129], v[174:177], v[114:117]
	v_mfma_f32_16x16x32_bf16 v[94:97], v[102:105], v[182:185], v[94:97]
	v_mfma_f32_16x16x32_bf16 v[90:93], v[126:129], v[182:185], v[90:93]
	v_mfma_f32_16x16x32_bf16 v[78:81], v[102:105], v[226:229], v[78:81]
	v_mfma_f32_16x16x32_bf16 v[74:77], v[126:129], v[226:229], v[74:77]
	v_mfma_f32_16x16x32_bf16 v[134:137], v[146:149], v[162:165], v[134:137]
	v_mfma_f32_16x16x32_bf16 v[130:133], v[154:157], v[162:165], v[130:133]
	v_mfma_f32_16x16x32_bf16 v[110:113], v[146:149], v[170:173], v[110:113]
	v_mfma_f32_16x16x32_bf16 v[106:109], v[154:157], v[170:173], v[106:109]
	v_mfma_f32_16x16x32_bf16 v[86:89], v[146:149], v[178:181], v[86:89]
	v_mfma_f32_16x16x32_bf16 v[82:85], v[154:157], v[178:181], v[82:85]
	v_mfma_f32_16x16x32_bf16 v[70:73], v[146:149], v[222:225], v[70:73]
	v_mfma_f32_16x16x32_bf16 v[66:69], v[154:157], v[222:225], v[66:69]
	v_mfma_f32_16x16x32_bf16 v[134:137], v[150:153], v[166:169], v[134:137]
	v_mfma_f32_16x16x32_bf16 v[130:133], v[158:161], v[166:169], v[130:133]
	v_mfma_f32_16x16x32_bf16 v[110:113], v[150:153], v[174:177], v[110:113]
	v_mfma_f32_16x16x32_bf16 v[106:109], v[158:161], v[174:177], v[106:109]
	v_mfma_f32_16x16x32_bf16 v[86:89], v[150:153], v[182:185], v[86:89]
	v_mfma_f32_16x16x32_bf16 v[82:85], v[158:161], v[182:185], v[82:85]
	v_mfma_f32_16x16x32_bf16 v[70:73], v[150:153], v[226:229], v[70:73]
	v_mfma_f32_16x16x32_bf16 v[66:69], v[158:161], v[226:229], v[66:69]
	s_barrier
; #define PG8_STAGE(bufoff, gbase, voff) do { _Pragma("unroll") for (int _i = 0; _i < 2; ++_i) \
;         __builtin_amdgcn_global_load_lds((const unsigned*)((const char*)(gbase) + (voff)[_i]), (PG8_LAS unsigned*)(lds + (bufoff) + ldsw + _i * 8192), 16, 0, 0); } while (0)
; #define PG8_LDA(dst, b, h) do { _Pragma("unroll") for (int m = 0; m < 4; ++m) _Pragma("unroll") for (int k = 0; k < 2; ++k) dst[m][k] = *(const PG8_LAS bf16x8*)(lds + PG8_SA(b, h) + aoff + m * 2048 + k * 1024); } while (0)
; #define PG8_MMA(ai, bj, At, Bt) do { __builtin_amdgcn_s_setprio(1); _Pragma("unroll") for (int m = 0; m < 4; ++m) _Pragma("unroll") for (int n = 0; n < 2; ++n) _Pragma("unroll") for (int k = 0; k < 2; ++k) \
;         acc[ai][bj][m][n] = __builtin_amdgcn_mfma_f32_16x16x32_bf16(Bt[n][k], At[m][k], acc[ai][bj][m][n], 0, 0, 0); __builtin_amdgcn_s_setprio(0); } while (0)
; #define PG8_WAIT_V(n) asm volatile("s_waitcnt vmcnt(" #n ")" ::: "memory")
; #define PG8_WAIT_L(n) asm volatile("s_waitcnt lgkmcnt(" #n ")" ::: "memory")
; #define PG8_BAR __builtin_amdgcn_s_barrier()
; #define PG8_SCHED __builtin_amdgcn_sched_barrier(0)
; template <class Epi, class Sched, bool ALIGN_EPI = false, bool SP2 = false>
; __device__ __forceinline__ void gemm_phase(PG8_LAS unsigned char* lds, const Gemm g, const Sched& S, const Epi& E) {
;     ...
;             PG8_LDA(At, 1, 1); PG8_STAGE(PG8_SB(1, 0), b3, voffB); PG8_STAGE(PG8_SB(1, 1), b3 + hstepB, voffB); PG8_STAGE(PG8_SA(1, 0), a3, voffA);
;             PG8_WAIT_V(8); PG8_WAIT_L(0); PG8_BAR; PG8_MMA(1, 0, At, B0); PG8_MMA(1, 1, At, B1); PG8_BAR; PG8_SCHED;
;     ...
;         if constexpr (ALIGN_EPI) { if (wr == 0) PG8_BAR; }
	s_setprio 0
	s_add_u32 s46, s44, 0x8000
	s_addc_u32 s47, s45, 0
	s_add_i32 s55, s55, s0
	v_lshl_add_u64 v[230:231], s[46:47], 0, v[188:189]
	s_mov_b32 m0, s55
	ds_read_b128 v[162:165], v217 offset:49152
	ds_read_b128 v[166:169], v217 offset:50176
	ds_read_b128 v[170:173], v217 offset:51200
	ds_read_b128 v[174:177], v217 offset:52224
	ds_read_b128 v[178:181], v217 offset:53248
	ds_read_b128 v[182:185], v217 offset:54272
	ds_read_b128 v[222:225], v217 offset:55296
	ds_read_b128 v[226:229], v217 offset:56320
	global_load_lds_dwordx4 v[230:231], off
	s_add_i32 m0, s55, 0x2000
	s_add_u32 s44, s44, 0x9000
	v_lshl_add_u64 v[230:231], s[46:47], 0, v[192:193]
	s_addc_u32 s45, s45, 0
	s_add_i32 s46, s67, s0
	global_load_lds_dwordx4 v[230:231], off
	v_lshl_add_u64 v[230:231], s[44:45], 0, v[188:189]
	s_mov_b32 m0, s46
	s_nop 0
	global_load_lds_dwordx4 v[230:231], off
	v_lshl_add_u64 v[230:231], s[44:45], 0, v[192:193]
	s_add_i32 m0, s46, 0x2000
	s_nop 0
	global_load_lds_dwordx4 v[230:231], off
	v_lshl_add_u64 v[230:231], s[42:43], 0, v[186:187]
	s_mov_b32 m0, s56
	s_nop 0
	global_load_lds_dwordx4 v[230:231], off
	v_lshl_add_u64 v[230:231], s[42:43], 0, v[190:191]
	s_mov_b32 m0, s57
	s_nop 0
	global_load_lds_dwordx4 v[230:231], off
	s_waitcnt vmcnt(8)
	s_waitcnt lgkmcnt(0)
	s_setprio 1
	s_barrier
	v_mfma_f32_16x16x32_bf16 v[62:65], v[98:101], v[162:165], v[62:65]
	v_mfma_f32_16x16x32_bf16 v[58:61], v[122:125], v[162:165], v[58:61]
	v_mfma_f32_16x16x32_bf16 v[46:49], v[98:101], v[170:173], v[46:49]
	v_mfma_f32_16x16x32_bf16 v[42:45], v[122:125], v[170:173], v[42:45]
	v_mfma_f32_16x16x32_bf16 v[30:33], v[98:101], v[178:181], v[30:33]
	v_mfma_f32_16x16x32_bf16 v[26:29], v[122:125], v[178:181], v[26:29]
	v_mfma_f32_16x16x32_bf16 v[14:17], v[98:101], v[222:225], v[14:17]
	v_mfma_f32_16x16x32_bf16 v[10:13], v[122:125], v[222:225], v[10:13]
	v_mfma_f32_16x16x32_bf16 v[62:65], v[102:105], v[166:169], v[62:65]
	v_mfma_f32_16x16x32_bf16 v[58:61], v[126:129], v[166:169], v[58:61]
	v_mfma_f32_16x16x32_bf16 v[46:49], v[102:105], v[174:177], v[46:49]
	v_mfma_f32_16x16x32_bf16 v[42:45], v[126:129], v[174:177], v[42:45]
	v_mfma_f32_16x16x32_bf16 v[30:33], v[102:105], v[182:185], v[30:33]
	v_mfma_f32_16x16x32_bf16 v[26:29], v[126:129], v[182:185], v[26:29]
	v_mfma_f32_16x16x32_bf16 v[14:17], v[102:105], v[226:229], v[14:17]
	v_mfma_f32_16x16x32_bf16 v[10:13], v[126:129], v[226:229], v[10:13]
	v_mfma_f32_16x16x32_bf16 v[54:57], v[146:149], v[162:165], v[54:57]
	v_mfma_f32_16x16x32_bf16 v[50:53], v[154:157], v[162:165], v[50:53]
	v_mfma_f32_16x16x32_bf16 v[38:41], v[146:149], v[170:173], v[38:41]
	v_mfma_f32_16x16x32_bf16 v[34:37], v[154:157], v[170:173], v[34:37]
	v_mfma_f32_16x16x32_bf16 v[22:25], v[146:149], v[178:181], v[22:25]
	v_mfma_f32_16x16x32_bf16 v[18:21], v[154:157], v[178:181], v[18:21]
	v_mfma_f32_16x16x32_bf16 v[6:9], v[146:149], v[222:225], v[6:9]
	v_mfma_f32_16x16x32_bf16 v[2:5], v[154:157], v[222:225], v[2:5]
	v_mfma_f32_16x16x32_bf16 v[54:57], v[150:153], v[166:169], v[54:57]
	v_mfma_f32_16x16x32_bf16 v[50:53], v[158:161], v[166:169], v[50:53]
	v_mfma_f32_16x16x32_bf16 v[38:41], v[150:153], v[174:177], v[38:41]
	v_mfma_f32_16x16x32_bf16 v[34:37], v[158:161], v[174:177], v[34:37]
	v_mfma_f32_16x16x32_bf16 v[22:25], v[150:153], v[182:185], v[22:25]
	v_mfma_f32_16x16x32_bf16 v[18:21], v[158:161], v[182:185], v[18:21]
	v_mfma_f32_16x16x32_bf16 v[6:9], v[150:153], v[226:229], v[6:9]
	v_mfma_f32_16x16x32_bf16 v[2:5], v[158:161], v[226:229], v[2:5]
	s_barrier
	s_setprio 0
	s_add_i32 s54, s54, 2
	s_add_u32 s36, s36, 0x10000
	s_addc_u32 s37, s37, 0
	s_add_u32 s52, s52, 0x10000
	s_addc_u32 s53, s53, 0
	s_cmp_gt_u32 s54, 61
	s_cbranch_scc0 .LBB0_682
	s_and_b64 vcc, exec, s[18:19]
	s_cbranch_vccz .LBB0_685
	s_barrier

; #define PG8_STAGE(bufoff, gbase, voff) do { _Pragma("unroll") for (int _i = 0; _i < 2; ++_i) \
;         __builtin_amdgcn_global_load_lds((const unsigned*)((const char*)(gbase) + (voff)[_i]), (PG8_LAS unsigned*)(lds + (bufoff) + ldsw + _i * 8192), 16, 0, 0); } while (0)
; #define PG8_LDA(dst, b, h) do { _Pragma("unroll") for (int m = 0; m < 4; ++m) _Pragma("unroll") for (int k = 0; k < 2; ++k) dst[m][k] = *(const PG8_LAS bf16x8*)(lds + PG8_SA(b, h) + aoff + m * 2048 + k * 1024); } while (0)
; #define PG8_LDB(dst, b, h) do { _Pragma("unroll") for (int n = 0; n < 2; ++n) _Pragma("unroll") for (int k = 0; k < 2; ++k) dst[n][k] = *(const PG8_LAS bf16x8*)(lds + PG8_SB(b, h) + boff + n * 2048 + k * 1024); } while (0)
; #define PG8_MMA(ai, bj, At, Bt) do { __builtin_amdgcn_s_setprio(1); _Pragma("unroll") for (int m = 0; m < 4; ++m) _Pragma("unroll") for (int n = 0; n < 2; ++n) _Pragma("unroll") for (int k = 0; k < 2; ++k) \
;         acc[ai][bj][m][n] = __builtin_amdgcn_mfma_f32_16x16x32_bf16(Bt[n][k], At[m][k], acc[ai][bj][m][n], 0, 0, 0); __builtin_amdgcn_s_setprio(0); } while (0)
; #define PG8_WAIT_V(n) asm volatile("s_waitcnt vmcnt(" #n ")" ::: "memory")
; #define PG8_WAIT_L(n) asm volatile("s_waitcnt lgkmcnt(" #n ")" ::: "memory")
; #define PG8_BAR __builtin_amdgcn_s_barrier()
; template <class Epi, class Sched, bool ALIGN_EPI = false, bool SP2 = false>
; __device__ __forceinline__ void gemm_phase(PG8_LAS unsigned char* lds, const Gemm g, const Sched& S, const Epi& E) {
;     ...
;             const char* a1 = cA + (size_t)(t + 1) * kstep;
;             const char* a2 = last ? nA : cA + (size_t)(t + 2) * kstep; const char* b2 = last ? nB : cB + (size_t)(t + 2) * kstep;
;             const char* a3 = a2 + kstep; const char* b3 = b2 + kstep;
;             if (last && has_next) S.a_ready(nxt);
;             if constexpr (SP2) {
;             PG8_LDB(B0, 0, 0); PG8_LDB(B1, 0, 1); PG8_SCHED; PG8_LDA(At, 0, 0); PG8_STAGE(PG8_SA(1, 1), a1 + hstep, voffA);
;             PG8_WAIT_V(8); PG8_WAIT_L(0); PG8_BAR; PG8_MMA(0, 0, At, B0); PG8_MMA(0, 1, At, B1); PG8_BAR; PG8_SCHED;
;             PG8_LDA(At, 0, 1); PG8_STAGE(PG8_SB(0, 0), b2, voffB); PG8_STAGE(PG8_SB(0, 1), b2 + hstepB, voffB); PG8_STAGE(PG8_SA(0, 0), a2, voffA);
;             PG8_WAIT_V(8); PG8_WAIT_L(0); PG8_BAR; PG8_MMA(1, 0, At, B0); PG8_MMA(1, 1, At, B1); PG8_BAR; PG8_SCHED;
.LBB0_726:
	ds_read_b128 v[130:133], v209
	ds_read_b128 v[134:137], v209 offset:1024
	ds_read_b128 v[138:141], v209 offset:2048
	ds_read_b128 v[142:145], v209 offset:3072
	ds_read_b128 v[146:149], v210
	ds_read_b128 v[150:153], v210 offset:1024
	ds_read_b128 v[154:157], v210 offset:2048
	ds_read_b128 v[158:161], v210 offset:3072
	s_add_u32 s54, s50, 0x4000
	s_addc_u32 s55, s51, 0
	s_cmp_eq_u32 s53, 60
	s_cselect_b32 s68, s29, s54
	s_cselect_b32 s69, s27, s55
	s_cselect_b32 s66, s47, s49
	s_cselect_b32 s67, s37, s52
	s_add_u32 s64, s68, 0x8000
	s_addc_u32 s65, s69, 0
	v_lshl_add_u64 v[206:207], s[50:51], 0, v[198:199]
	s_add_i32 m0, s1, 0xc000
	ds_read_b128 v[162:165], v211
	ds_read_b128 v[166:169], v211 offset:1024
	ds_read_b128 v[170:173], v211 offset:2048
	ds_read_b128 v[174:177], v211 offset:3072
	ds_read_b128 v[178:181], v211 offset:4096
	ds_read_b128 v[182:185], v211 offset:5120
	ds_read_b128 v[224:227], v211 offset:6144
	ds_read_b128 v[228:231], v211 offset:7168
	global_load_lds_dwordx4 v[206:207], off
	v_lshl_add_u64 v[206:207], s[50:51], 0, v[200:201]
	s_add_i32 m0, s1, 0xe000
	s_nop 0
	global_load_lds_dwordx4 v[206:207], off
	s_waitcnt vmcnt(8)
	s_waitcnt lgkmcnt(0)
	s_setprio 1
	s_barrier
	v_mfma_f32_16x16x32_bf16 v[126:129], v[130:133], v[162:165], v[126:129]
	v_mfma_f32_16x16x32_bf16 v[122:125], v[138:141], v[162:165], v[122:125]
	v_mfma_f32_16x16x32_bf16 v[110:113], v[130:133], v[170:173], v[110:113]
	v_mfma_f32_16x16x32_bf16 v[106:109], v[138:141], v[170:173], v[106:109]
	v_mfma_f32_16x16x32_bf16 v[94:97], v[130:133], v[178:181], v[94:97]
	v_mfma_f32_16x16x32_bf16 v[90:93], v[138:141], v[178:181], v[90:93]
	v_mfma_f32_16x16x32_bf16 v[78:81], v[130:133], v[224:227], v[78:81]
	v_mfma_f32_16x16x32_bf16 v[74:77], v[138:141], v[224:227], v[74:77]
	v_mfma_f32_16x16x32_bf16 v[126:129], v[134:137], v[166:169], v[126:129]
	v_mfma_f32_16x16x32_bf16 v[122:125], v[142:145], v[166:169], v[122:125]
	v_mfma_f32_16x16x32_bf16 v[110:113], v[134:137], v[174:177], v[110:113]
	v_mfma_f32_16x16x32_bf16 v[106:109], v[142:145], v[174:177], v[106:109]
	v_mfma_f32_16x16x32_bf16 v[94:97], v[134:137], v[182:185], v[94:97]
	v_mfma_f32_16x16x32_bf16 v[90:93], v[142:145], v[182:185], v[90:93]
	v_mfma_f32_16x16x32_bf16 v[78:81], v[134:137], v[228:231], v[78:81]
	v_mfma_f32_16x16x32_bf16 v[74:77], v[142:145], v[228:231], v[74:77]
	v_mfma_f32_16x16x32_bf16 v[118:121], v[146:149], v[162:165], v[118:121]
	v_mfma_f32_16x16x32_bf16 v[114:117], v[154:157], v[162:165], v[114:117]
	v_mfma_f32_16x16x32_bf16 v[102:105], v[146:149], v[170:173], v[102:105]
	v_mfma_f32_16x16x32_bf16 v[98:101], v[154:157], v[170:173], v[98:101]
	v_mfma_f32_16x16x32_bf16 v[86:89], v[146:149], v[178:181], v[86:89]
	v_mfma_f32_16x16x32_bf16 v[82:85], v[154:157], v[178:181], v[82:85]
	v_mfma_f32_16x16x32_bf16 v[70:73], v[146:149], v[224:227], v[70:73]
	v_mfma_f32_16x16x32_bf16 v[66:69], v[154:157], v[224:227], v[66:69]
	v_mfma_f32_16x16x32_bf16 v[118:121], v[150:153], v[166:169], v[118:121]
	v_mfma_f32_16x16x32_bf16 v[114:117], v[158:161], v[166:169], v[114:117]
	v_mfma_f32_16x16x32_bf16 v[102:105], v[150:153], v[174:177], v[102:105]
	v_mfma_f32_16x16x32_bf16 v[98:101], v[158:161], v[174:177], v[98:101]
	v_mfma_f32_16x16x32_bf16 v[86:89], v[150:153], v[182:185], v[86:89]
	v_mfma_f32_16x16x32_bf16 v[82:85], v[158:161], v[182:185], v[82:85]
	v_mfma_f32_16x16x32_bf16 v[70:73], v[150:153], v[228:231], v[70:73]
	v_mfma_f32_16x16x32_bf16 v[66:69], v[158:161], v[228:231], v[66:69]
	s_barrier
	s_setprio 0
	s_add_i32 s54, s74, s0
	v_lshl_add_u64 v[206:207], s[66:67], 0, v[188:189]
	s_mov_b32 m0, s54
	ds_read_b128 v[162:165], v211 offset:16384
	ds_read_b128 v[166:169], v211 offset:17408
	ds_read_b128 v[170:173], v211 offset:18432
	ds_read_b128 v[174:177], v211 offset:19456
	ds_read_b128 v[178:181], v211 offset:20480
	ds_read_b128 v[182:185], v211 offset:21504
	ds_read_b128 v[224:227], v211 offset:22528
	ds_read_b128 v[228:231], v211 offset:23552
	global_load_lds_dwordx4 v[206:207], off
	s_add_i32 m0, s54, 0x2000
	s_add_u32 s54, s66, 0x1000
	v_lshl_add_u64 v[206:207], s[66:67], 0, v[192:193]
	s_addc_u32 s55, s67, 0
	s_add_i32 s89, s75, s0
	global_load_lds_dwordx4 v[206:207], off
	v_lshl_add_u64 v[206:207], s[54:55], 0, v[188:189]
	s_mov_b32 m0, s89
	s_nop 0
	global_load_lds_dwordx4 v[206:207], off
	v_lshl_add_u64 v[206:207], s[54:55], 0, v[192:193]
	s_add_i32 m0, s89, 0x2000
	s_nop 0
	global_load_lds_dwordx4 v[206:207], off
	v_lshl_add_u64 v[206:207], s[68:69], 0, v[186:187]
	s_mov_b32 m0, s1
	s_nop 0
	global_load_lds_dwordx4 v[206:207], off
	v_lshl_add_u64 v[206:207], s[68:69], 0, v[190:191]
	s_mov_b32 m0, s3
	s_nop 0
	global_load_lds_dwordx4 v[206:207], off
	s_waitcnt vmcnt(8)
	s_waitcnt lgkmcnt(0)
	s_setprio 1
	s_barrier
; #define PG8_STAGE(bufoff, gbase, voff) do { _Pragma("unroll") for (int _i = 0; _i < 2; ++_i) \
;         __builtin_amdgcn_global_load_lds((const unsigned*)((const char*)(gbase) + (voff)[_i]), (PG8_LAS unsigned*)(lds + (bufoff) + ldsw + _i * 8192), 16, 0, 0); } while (0)
; #define PG8_LDA(dst, b, h) do { _Pragma("unroll") for (int m = 0; m < 4; ++m) _Pragma("unroll") for (int k = 0; k < 2; ++k) dst[m][k] = *(const PG8_LAS bf16x8*)(lds + PG8_SA(b, h) + aoff + m * 2048 + k * 1024); } while (0)
; #define PG8_LDB(dst, b, h) do { _Pragma("unroll") for (int n = 0; n < 2; ++n) _Pragma("unroll") for (int k = 0; k < 2; ++k) dst[n][k] = *(const PG8_LAS bf16x8*)(lds + PG8_SB(b, h) + boff + n * 2048 + k * 1024); } while (0)
; #define PG8_MMA(ai, bj, At, Bt) do { __builtin_amdgcn_s_setprio(1); _Pragma("unroll") for (int m = 0; m < 4; ++m) _Pragma("unroll") for (int n = 0; n < 2; ++n) _Pragma("unroll") for (int k = 0; k < 2; ++k) \
;         acc[ai][bj][m][n] = __builtin_amdgcn_mfma_f32_16x16x32_bf16(Bt[n][k], At[m][k], acc[ai][bj][m][n], 0, 0, 0); __builtin_amdgcn_s_setprio(0); } while (0)
; #define PG8_WAIT_V(n) asm volatile("s_waitcnt vmcnt(" #n ")" ::: "memory")
; #define PG8_WAIT_L(n) asm volatile("s_waitcnt lgkmcnt(" #n ")" ::: "memory")
; #define PG8_BAR __builtin_amdgcn_s_barrier()
; #define PG8_SCHED __builtin_amdgcn_sched_barrier(0)
; template <class Epi, class Sched, bool ALIGN_EPI = false, bool SP2 = false>
; __device__ __forceinline__ void gemm_phase(PG8_LAS unsigned char* lds, const Gemm g, const Sched& S, const Epi& E) {
;     ...
;             PG8_WAIT_V(8); PG8_WAIT_L(0); PG8_BAR; PG8_MMA(1, 0, At, B0); PG8_MMA(1, 1, At, B1); PG8_BAR; PG8_SCHED;
;             PG8_LDB(B0, 1, 0); PG8_LDB(B1, 1, 1); PG8_SCHED; PG8_LDA(At, 1, 0); PG8_STAGE(PG8_SA(0, 1), a2 + hstep, voffA);
;             PG8_WAIT_V(8); PG8_WAIT_L(0); PG8_BAR; PG8_MMA(0, 0, At, B0); PG8_MMA(0, 1, At, B1); PG8_BAR; PG8_SCHED;
	v_mfma_f32_16x16x32_bf16 v[62:65], v[130:133], v[162:165], v[62:65]
	v_mfma_f32_16x16x32_bf16 v[58:61], v[138:141], v[162:165], v[58:61]
	v_mfma_f32_16x16x32_bf16 v[46:49], v[130:133], v[170:173], v[46:49]
	v_mfma_f32_16x16x32_bf16 v[42:45], v[138:141], v[170:173], v[42:45]
	v_mfma_f32_16x16x32_bf16 v[30:33], v[130:133], v[178:181], v[30:33]
	v_mfma_f32_16x16x32_bf16 v[26:29], v[138:141], v[178:181], v[26:29]
	v_mfma_f32_16x16x32_bf16 v[14:17], v[130:133], v[224:227], v[14:17]
	v_mfma_f32_16x16x32_bf16 v[10:13], v[138:141], v[224:227], v[10:13]
	v_mfma_f32_16x16x32_bf16 v[62:65], v[134:137], v[166:169], v[62:65]
	v_mfma_f32_16x16x32_bf16 v[58:61], v[142:145], v[166:169], v[58:61]
	v_mfma_f32_16x16x32_bf16 v[46:49], v[134:137], v[174:177], v[46:49]
	v_mfma_f32_16x16x32_bf16 v[42:45], v[142:145], v[174:177], v[42:45]
	v_mfma_f32_16x16x32_bf16 v[30:33], v[134:137], v[182:185], v[30:33]
	v_mfma_f32_16x16x32_bf16 v[26:29], v[142:145], v[182:185], v[26:29]
	v_mfma_f32_16x16x32_bf16 v[14:17], v[134:137], v[228:231], v[14:17]
	v_mfma_f32_16x16x32_bf16 v[10:13], v[142:145], v[228:231], v[10:13]
	v_mfma_f32_16x16x32_bf16 v[54:57], v[146:149], v[162:165], v[54:57]
	v_mfma_f32_16x16x32_bf16 v[50:53], v[154:157], v[162:165], v[50:53]
	v_mfma_f32_16x16x32_bf16 v[38:41], v[146:149], v[170:173], v[38:41]
	v_mfma_f32_16x16x32_bf16 v[34:37], v[154:157], v[170:173], v[34:37]
	v_mfma_f32_16x16x32_bf16 v[22:25], v[146:149], v[178:181], v[22:25]
	v_mfma_f32_16x16x32_bf16 v[18:21], v[154:157], v[178:181], v[18:21]
	v_mfma_f32_16x16x32_bf16 v[6:9], v[146:149], v[224:227], v[6:9]
	v_mfma_f32_16x16x32_bf16 v[2:5], v[154:157], v[224:227], v[2:5]
	v_mfma_f32_16x16x32_bf16 v[54:57], v[150:153], v[166:169], v[54:57]
	v_mfma_f32_16x16x32_bf16 v[50:53], v[158:161], v[166:169], v[50:53]
	v_mfma_f32_16x16x32_bf16 v[38:41], v[150:153], v[174:177], v[38:41]
	v_mfma_f32_16x16x32_bf16 v[34:37], v[158:161], v[174:177], v[34:37]
	v_mfma_f32_16x16x32_bf16 v[22:25], v[150:153], v[182:185], v[22:25]
	v_mfma_f32_16x16x32_bf16 v[18:21], v[158:161], v[182:185], v[18:21]
	v_mfma_f32_16x16x32_bf16 v[6:9], v[150:153], v[228:231], v[6:9]
	v_mfma_f32_16x16x32_bf16 v[2:5], v[158:161], v[228:231], v[2:5]
	s_barrier
	s_setprio 0
	s_add_i32 s89, 0, 0x18000
	s_add_i32 s90, 0, 0x1c000
	v_add_u32_e32 v142, s89, v214
	v_add_u32_e32 v158, s90, v214
	ds_read_b128 v[130:133], v142
	ds_read_b128 v[134:137], v142 offset:1024
	ds_read_b128 v[138:141], v142 offset:2048
	ds_read_b128 v[142:145], v142 offset:3072
	ds_read_b128 v[146:149], v158
	ds_read_b128 v[150:153], v158 offset:1024
	ds_read_b128 v[154:157], v158 offset:2048
	ds_read_b128 v[158:161], v158 offset:3072
	s_add_u32 s54, s68, 0x4000
	s_addc_u32 s55, s69, 0
	s_mov_b32 m0, s56
	v_lshl_add_u64 v[206:207], s[54:55], 0, v[186:187]
	ds_read_b128 v[162:165], v211 offset:32768
	ds_read_b128 v[166:169], v211 offset:33792
	ds_read_b128 v[170:173], v211 offset:34816
	ds_read_b128 v[174:177], v211 offset:35840
	ds_read_b128 v[178:181], v211 offset:36864
	ds_read_b128 v[182:185], v211 offset:37888
	ds_read_b128 v[224:227], v211 offset:38912
	ds_read_b128 v[228:231], v211 offset:39936
	global_load_lds_dwordx4 v[206:207], off
	v_lshl_add_u64 v[206:207], s[54:55], 0, v[190:191]
	s_mov_b32 m0, s57
	s_nop 0
	global_load_lds_dwordx4 v[206:207], off
	s_waitcnt vmcnt(8)
	s_waitcnt lgkmcnt(0)
	s_setprio 1
	s_barrier
	v_mfma_f32_16x16x32_bf16 v[126:129], v[130:133], v[162:165], v[126:129]
	v_mfma_f32_16x16x32_bf16 v[122:125], v[138:141], v[162:165], v[122:125]
	v_mfma_f32_16x16x32_bf16 v[110:113], v[130:133], v[170:173], v[110:113]
	v_mfma_f32_16x16x32_bf16 v[106:109], v[138:141], v[170:173], v[106:109]
	v_mfma_f32_16x16x32_bf16 v[94:97], v[130:133], v[178:181], v[94:97]
	v_mfma_f32_16x16x32_bf16 v[90:93], v[138:141], v[178:181], v[90:93]
	v_mfma_f32_16x16x32_bf16 v[78:81], v[130:133], v[224:227], v[78:81]
	v_mfma_f32_16x16x32_bf16 v[74:77], v[138:141], v[224:227], v[74:77]
	v_mfma_f32_16x16x32_bf16 v[126:129], v[134:137], v[166:169], v[126:129]
	v_mfma_f32_16x16x32_bf16 v[122:125], v[142:145], v[166:169], v[122:125]
	v_mfma_f32_16x16x32_bf16 v[110:113], v[134:137], v[174:177], v[110:113]
	v_mfma_f32_16x16x32_bf16 v[106:109], v[142:145], v[174:177], v[106:109]
	v_mfma_f32_16x16x32_bf16 v[94:97], v[134:137], v[182:185], v[94:97]
	v_mfma_f32_16x16x32_bf16 v[90:93], v[142:145], v[182:185], v[90:93]
	v_mfma_f32_16x16x32_bf16 v[78:81], v[134:137], v[228:231], v[78:81]
	v_mfma_f32_16x16x32_bf16 v[74:77], v[142:145], v[228:231], v[74:77]
	v_mfma_f32_16x16x32_bf16 v[118:121], v[146:149], v[162:165], v[118:121]
	v_mfma_f32_16x16x32_bf16 v[114:117], v[154:157], v[162:165], v[114:117]
	v_mfma_f32_16x16x32_bf16 v[102:105], v[146:149], v[170:173], v[102:105]
	v_mfma_f32_16x16x32_bf16 v[98:101], v[154:157], v[170:173], v[98:101]
	v_mfma_f32_16x16x32_bf16 v[86:89], v[146:149], v[178:181], v[86:89]
	v_mfma_f32_16x16x32_bf16 v[82:85], v[154:157], v[178:181], v[82:85]
	v_mfma_f32_16x16x32_bf16 v[70:73], v[146:149], v[224:227], v[70:73]
	v_mfma_f32_16x16x32_bf16 v[66:69], v[154:157], v[224:227], v[66:69]
	v_mfma_f32_16x16x32_bf16 v[118:121], v[150:153], v[166:169], v[118:121]
	v_mfma_f32_16x16x32_bf16 v[114:117], v[158:161], v[166:169], v[114:117]
	v_mfma_f32_16x16x32_bf16 v[102:105], v[150:153], v[174:177], v[102:105]
	v_mfma_f32_16x16x32_bf16 v[98:101], v[158:161], v[174:177], v[98:101]
	v_mfma_f32_16x16x32_bf16 v[86:89], v[150:153], v[182:185], v[86:89]
	v_mfma_f32_16x16x32_bf16 v[82:85], v[158:161], v[182:185], v[82:85]
	v_mfma_f32_16x16x32_bf16 v[70:73], v[150:153], v[228:231], v[70:73]
	v_mfma_f32_16x16x32_bf16 v[66:69], v[158:161], v[228:231], v[66:69]
	s_barrier
; #define PG8_STAGE(bufoff, gbase, voff) do { _Pragma("unroll") for (int _i = 0; _i < 2; ++_i) \
;         __builtin_amdgcn_global_load_lds((const unsigned*)((const char*)(gbase) + (voff)[_i]), (PG8_LAS unsigned*)(lds + (bufoff) + ldsw + _i * 8192), 16, 0, 0); } while (0)
; #define PG8_LDA(dst, b, h) do { _Pragma("unroll") for (int m = 0; m < 4; ++m) _Pragma("unroll") for (int k = 0; k < 2; ++k) dst[m][k] = *(const PG8_LAS bf16x8*)(lds + PG8_SA(b, h) + aoff + m * 2048 + k * 1024); } while (0)
; #define PG8_MMA(ai, bj, At, Bt) do { __builtin_amdgcn_s_setprio(1); _Pragma("unroll") for (int m = 0; m < 4; ++m) _Pragma("unroll") for (int n = 0; n < 2; ++n) _Pragma("unroll") for (int k = 0; k < 2; ++k) \
;         acc[ai][bj][m][n] = __builtin_amdgcn_mfma_f32_16x16x32_bf16(Bt[n][k], At[m][k], acc[ai][bj][m][n], 0, 0, 0); __builtin_amdgcn_s_setprio(0); } while (0)
; #define PG8_WAIT_V(n) asm volatile("s_waitcnt vmcnt(" #n ")" ::: "memory")
; #define PG8_WAIT_L(n) asm volatile("s_waitcnt lgkmcnt(" #n ")" ::: "memory")
; #define PG8_BAR __builtin_amdgcn_s_barrier()
; #define PG8_SCHED __builtin_amdgcn_sched_barrier(0)
; template <class Epi, class Sched, bool ALIGN_EPI = false, bool SP2 = false>
; __device__ __forceinline__ void gemm_phase(PG8_LAS unsigned char* lds, const Gemm g, const Sched& S, const Epi& E) {
;     ...
;             PG8_LDA(At, 1, 1); PG8_STAGE(PG8_SB(1, 0), b3, voffB); PG8_STAGE(PG8_SB(1, 1), b3 + hstepB, voffB); PG8_STAGE(PG8_SA(1, 0), a3, voffA);
;             PG8_WAIT_V(8); PG8_WAIT_L(0); PG8_BAR; PG8_MMA(1, 0, At, B0); PG8_MMA(1, 1, At, B1); PG8_BAR; PG8_SCHED;
;     ...
;         if constexpr (ALIGN_EPI) { if (wr == 0) PG8_BAR; }
	s_setprio 0
	s_add_u32 s54, s66, 0x8000
	s_addc_u32 s55, s67, 0
	s_add_i32 s68, s89, s0
	v_lshl_add_u64 v[206:207], s[54:55], 0, v[188:189]
	s_mov_b32 m0, s68
	ds_read_b128 v[162:165], v211 offset:49152
	ds_read_b128 v[166:169], v211 offset:50176
	ds_read_b128 v[170:173], v211 offset:51200
	ds_read_b128 v[174:177], v211 offset:52224
	ds_read_b128 v[178:181], v211 offset:53248
	ds_read_b128 v[182:185], v211 offset:54272
	ds_read_b128 v[224:227], v211 offset:55296
	ds_read_b128 v[228:231], v211 offset:56320
	global_load_lds_dwordx4 v[206:207], off
	s_add_i32 m0, s68, 0x2000
	v_lshl_add_u64 v[206:207], s[54:55], 0, v[192:193]
	s_add_u32 s54, s66, 0x9000
	s_addc_u32 s55, s67, 0
	s_add_i32 s66, s90, s0
	global_load_lds_dwordx4 v[206:207], off
	v_lshl_add_u64 v[206:207], s[54:55], 0, v[188:189]
	s_mov_b32 m0, s66
	s_nop 0
	global_load_lds_dwordx4 v[206:207], off
	v_lshl_add_u64 v[206:207], s[54:55], 0, v[192:193]
	s_add_i32 m0, s66, 0x2000
	s_nop 0
	global_load_lds_dwordx4 v[206:207], off
	v_lshl_add_u64 v[206:207], s[64:65], 0, v[186:187]
	s_mov_b32 m0, s71
	s_nop 0
	global_load_lds_dwordx4 v[206:207], off
	v_lshl_add_u64 v[206:207], s[64:65], 0, v[190:191]
	s_mov_b32 m0, s72
	s_nop 0
	global_load_lds_dwordx4 v[206:207], off
	s_waitcnt vmcnt(8)
	s_waitcnt lgkmcnt(0)
	s_setprio 1
	s_barrier
	v_mfma_f32_16x16x32_bf16 v[62:65], v[130:133], v[162:165], v[62:65]
	v_mfma_f32_16x16x32_bf16 v[58:61], v[138:141], v[162:165], v[58:61]
	v_mfma_f32_16x16x32_bf16 v[46:49], v[130:133], v[170:173], v[46:49]
	v_mfma_f32_16x16x32_bf16 v[42:45], v[138:141], v[170:173], v[42:45]
	v_mfma_f32_16x16x32_bf16 v[30:33], v[130:133], v[178:181], v[30:33]
	v_mfma_f32_16x16x32_bf16 v[26:29], v[138:141], v[178:181], v[26:29]
	v_mfma_f32_16x16x32_bf16 v[14:17], v[130:133], v[224:227], v[14:17]
	v_mfma_f32_16x16x32_bf16 v[10:13], v[138:141], v[224:227], v[10:13]
	v_mfma_f32_16x16x32_bf16 v[62:65], v[134:137], v[166:169], v[62:65]
	v_mfma_f32_16x16x32_bf16 v[58:61], v[142:145], v[166:169], v[58:61]
	v_mfma_f32_16x16x32_bf16 v[46:49], v[134:137], v[174:177], v[46:49]
	v_mfma_f32_16x16x32_bf16 v[42:45], v[142:145], v[174:177], v[42:45]
	v_mfma_f32_16x16x32_bf16 v[30:33], v[134:137], v[182:185], v[30:33]
	v_mfma_f32_16x16x32_bf16 v[26:29], v[142:145], v[182:185], v[26:29]
	v_mfma_f32_16x16x32_bf16 v[14:17], v[134:137], v[228:231], v[14:17]
	v_mfma_f32_16x16x32_bf16 v[10:13], v[142:145], v[228:231], v[10:13]
	v_mfma_f32_16x16x32_bf16 v[54:57], v[146:149], v[162:165], v[54:57]
	v_mfma_f32_16x16x32_bf16 v[50:53], v[154:157], v[162:165], v[50:53]
	v_mfma_f32_16x16x32_bf16 v[38:41], v[146:149], v[170:173], v[38:41]
	v_mfma_f32_16x16x32_bf16 v[34:37], v[154:157], v[170:173], v[34:37]
	v_mfma_f32_16x16x32_bf16 v[22:25], v[146:149], v[178:181], v[22:25]
	v_mfma_f32_16x16x32_bf16 v[18:21], v[154:157], v[178:181], v[18:21]
	v_mfma_f32_16x16x32_bf16 v[6:9], v[146:149], v[224:227], v[6:9]
	v_mfma_f32_16x16x32_bf16 v[2:5], v[154:157], v[224:227], v[2:5]
	v_mfma_f32_16x16x32_bf16 v[54:57], v[150:153], v[166:169], v[54:57]
	v_mfma_f32_16x16x32_bf16 v[50:53], v[158:161], v[166:169], v[50:53]
	v_mfma_f32_16x16x32_bf16 v[38:41], v[150:153], v[174:177], v[38:41]
	v_mfma_f32_16x16x32_bf16 v[34:37], v[158:161], v[174:177], v[34:37]
	v_mfma_f32_16x16x32_bf16 v[22:25], v[150:153], v[182:185], v[22:25]
	v_mfma_f32_16x16x32_bf16 v[18:21], v[158:161], v[182:185], v[18:21]
	v_mfma_f32_16x16x32_bf16 v[6:9], v[150:153], v[228:231], v[6:9]
	v_mfma_f32_16x16x32_bf16 v[2:5], v[158:161], v[228:231], v[2:5]
	s_barrier
	s_setprio 0
	s_add_i32 s53, s53, 2
	s_add_u32 s50, s50, 0x10000
	s_addc_u32 s51, s51, 0
	s_add_u32 s49, s49, 0x10000
	s_addc_u32 s52, s52, 0
	s_cmp_gt_u32 s53, 61
	s_cbranch_scc0 .LBB0_726
	s_and_b64 vcc, exec, s[20:21]
	s_cbranch_vccz .LBB0_729
	s_barrier
